# v89 + knop2: K-loop m0->LDS-DMA wait states filled by the segment's own ds_read_b128 instead of s_nop 0 (60 nops removed)
# speedup vs baseline: 1.0167x; 1.0083x over previous
.LBB0_367:
	s_ashr_i32 s55, s54, 31
	s_lshl_b64 s[2:3], s[54:55], 19
	s_add_u32 s58, s4, s2
	s_addc_u32 s59, s5, s3
	s_and_b64 s[2:3], s[56:57], exec
	s_cselect_b32 s2, s59, s7
	s_cselect_b32 s3, s58, s6
	s_ashr_i32 s53, s52, 31
	s_lshl_b64 s[10:11], s[52:53], 19
	s_add_u32 s60, s15, s10
	s_addc_u32 s61, s78, s11
	s_and_b64 s[10:11], s[56:57], exec
	s_cselect_b32 s12, s61, s9
	s_cselect_b32 s13, s60, s8
	s_add_u32 s6, s6, 0x40080
	s_addc_u32 s7, s7, 0
	s_add_u32 s24, s8, 0x100
	s_addc_u32 s25, s9, 0
	s_mov_b32 s26, -2
	v_add_u32_e32 v254, 0x18000, v173
	v_add_u32_e32 v255, 0x1c000, v173
	ds_read_b128 v[114:117], v197
	ds_read_b128 v[134:137], v197 offset:1024
	ds_read_b128 v[138:141], v197 offset:2048
	ds_read_b128 v[142:145], v197 offset:3072
	ds_read_b128 v[146:149], v198
	ds_read_b128 v[150:153], v198 offset:1024
	ds_read_b128 v[154:157], v198 offset:2048
	ds_read_b128 v[158:161], v198 offset:3072
	s_add_u32 s0, s6, 0xfffc0080
	s_addc_u32 s8, s7, -1
	s_cmp_eq_u32 s26, 12
	s_cselect_b32 s11, s2, s8
	s_cselect_b32 s10, s3, s0
	s_cselect_b32 s9, s12, s25
	s_cselect_b32 s8, s13, s24
	s_add_i32 m0, s31, 0xc000
	ds_read_b128 v[184:187], v199
	ds_read_b128 v[188:191], v199 offset:1024
	ds_read_b128 v[206:209], v199 offset:2048
	ds_read_b128 v[210:213], v199 offset:3072
	ds_read_b128 v[214:217], v199 offset:4096
	ds_read_b128 v[218:221], v199 offset:5120
	ds_read_b128 v[222:225], v199 offset:6144
	global_load_lds_dwordx4 v180, s[6:7]
	s_add_i32 m0, s31, 0xe000
	ds_read_b128 v[226:229], v199 offset:7168
	global_load_lds_dwordx4 v182, s[6:7]
	s_waitcnt vmcnt(8)
	s_waitcnt lgkmcnt(0)
	s_barrier
	s_setprio 1
	v_mfma_f32_16x16x32_bf16 v[130:133], v[114:117], v[184:187], 0
	v_mfma_f32_16x16x32_bf16 v[126:129], v[138:141], v[184:187], 0
	v_mfma_f32_16x16x32_bf16 v[110:113], v[114:117], v[206:209], 0
	v_mfma_f32_16x16x32_bf16 v[106:109], v[138:141], v[206:209], 0
	v_mfma_f32_16x16x32_bf16 v[94:97], v[114:117], v[214:217], 0
	v_mfma_f32_16x16x32_bf16 v[90:93], v[138:141], v[214:217], 0
	v_mfma_f32_16x16x32_bf16 v[78:81], v[114:117], v[222:225], 0
	v_mfma_f32_16x16x32_bf16 v[74:77], v[138:141], v[222:225], 0
	v_mfma_f32_16x16x32_bf16 v[130:133], v[134:137], v[188:191], v[130:133]
	v_mfma_f32_16x16x32_bf16 v[126:129], v[142:145], v[188:191], v[126:129]
	v_mfma_f32_16x16x32_bf16 v[110:113], v[134:137], v[210:213], v[110:113]
	v_mfma_f32_16x16x32_bf16 v[106:109], v[142:145], v[210:213], v[106:109]
	v_mfma_f32_16x16x32_bf16 v[94:97], v[134:137], v[218:221], v[94:97]
	v_mfma_f32_16x16x32_bf16 v[90:93], v[142:145], v[218:221], v[90:93]
	v_mfma_f32_16x16x32_bf16 v[78:81], v[134:137], v[226:229], v[78:81]
	v_mfma_f32_16x16x32_bf16 v[74:77], v[142:145], v[226:229], v[74:77]
	v_mfma_f32_16x16x32_bf16 v[122:125], v[146:149], v[184:187], 0
	v_mfma_f32_16x16x32_bf16 v[118:121], v[154:157], v[184:187], 0
	v_mfma_f32_16x16x32_bf16 v[102:105], v[146:149], v[206:209], 0
	v_mfma_f32_16x16x32_bf16 v[98:101], v[154:157], v[206:209], 0
	v_mfma_f32_16x16x32_bf16 v[86:89], v[146:149], v[214:217], 0
	v_mfma_f32_16x16x32_bf16 v[82:85], v[154:157], v[214:217], 0
	v_mfma_f32_16x16x32_bf16 v[70:73], v[146:149], v[222:225], 0
	v_mfma_f32_16x16x32_bf16 v[66:69], v[154:157], v[222:225], 0
	v_mfma_f32_16x16x32_bf16 v[122:125], v[150:153], v[188:191], v[122:125]
	v_mfma_f32_16x16x32_bf16 v[118:121], v[158:161], v[188:191], v[118:121]
	v_mfma_f32_16x16x32_bf16 v[102:105], v[150:153], v[210:213], v[102:105]
	v_mfma_f32_16x16x32_bf16 v[98:101], v[158:161], v[210:213], v[98:101]
	v_mfma_f32_16x16x32_bf16 v[86:89], v[150:153], v[218:221], v[86:89]
	v_mfma_f32_16x16x32_bf16 v[82:85], v[158:161], v[218:221], v[82:85]
	v_mfma_f32_16x16x32_bf16 v[70:73], v[150:153], v[226:229], v[70:73]
	v_mfma_f32_16x16x32_bf16 v[66:69], v[158:161], v[226:229], v[66:69]
	s_setprio 0
	s_barrier
	s_add_i32 s0, s89, s79
	s_mov_b32 m0, s0
	ds_read_b128 v[184:187], v199 offset:16384
	ds_read_b128 v[188:191], v199 offset:17408
	ds_read_b128 v[206:209], v199 offset:18432
	ds_read_b128 v[210:213], v199 offset:19456
	global_load_lds_dwordx4 v164, s[8:9]
	s_add_i32 m0, s0, 0x2000
	s_add_u32 s62, s8, 0x40000
	s_addc_u32 s63, s9, 0
	s_add_i32 s0, s90, s79
	global_load_lds_dwordx4 v168, s[8:9]
	s_mov_b32 m0, s0
	ds_read_b128 v[214:217], v199 offset:20480
	global_load_lds_dwordx4 v164, s[62:63]
	s_add_i32 m0, s0, 0x2000
	ds_read_b128 v[218:221], v199 offset:21504
	global_load_lds_dwordx4 v168, s[62:63]
	s_mov_b32 m0, s31
	ds_read_b128 v[222:225], v199 offset:22528
	global_load_lds_dwordx4 v162, s[10:11]
	s_mov_b32 m0, s80
	ds_read_b128 v[226:229], v199 offset:23552
	global_load_lds_dwordx4 v166, s[10:11]
	s_waitcnt vmcnt(8)
	s_waitcnt lgkmcnt(0)
	s_barrier
	s_setprio 1
	v_mfma_f32_16x16x32_bf16 v[62:65], v[114:117], v[184:187], 0
	v_mfma_f32_16x16x32_bf16 v[58:61], v[138:141], v[184:187], 0
	v_mfma_f32_16x16x32_bf16 v[46:49], v[114:117], v[206:209], 0
	v_mfma_f32_16x16x32_bf16 v[42:45], v[138:141], v[206:209], 0
	v_mfma_f32_16x16x32_bf16 v[30:33], v[114:117], v[214:217], 0
	v_mfma_f32_16x16x32_bf16 v[26:29], v[138:141], v[214:217], 0
	v_mfma_f32_16x16x32_bf16 v[14:17], v[114:117], v[222:225], 0
	v_mfma_f32_16x16x32_bf16 v[10:13], v[138:141], v[222:225], 0
	v_mfma_f32_16x16x32_bf16 v[62:65], v[134:137], v[188:191], v[62:65]
	v_mfma_f32_16x16x32_bf16 v[58:61], v[142:145], v[188:191], v[58:61]
	v_mfma_f32_16x16x32_bf16 v[46:49], v[134:137], v[210:213], v[46:49]
	v_mfma_f32_16x16x32_bf16 v[42:45], v[142:145], v[210:213], v[42:45]
	v_mfma_f32_16x16x32_bf16 v[30:33], v[134:137], v[218:221], v[30:33]
	v_mfma_f32_16x16x32_bf16 v[26:29], v[142:145], v[218:221], v[26:29]
	v_mfma_f32_16x16x32_bf16 v[14:17], v[134:137], v[226:229], v[14:17]
	v_mfma_f32_16x16x32_bf16 v[10:13], v[142:145], v[226:229], v[10:13]
	v_mfma_f32_16x16x32_bf16 v[54:57], v[146:149], v[184:187], 0
	v_mfma_f32_16x16x32_bf16 v[50:53], v[154:157], v[184:187], 0
	v_mfma_f32_16x16x32_bf16 v[38:41], v[146:149], v[206:209], 0
	v_mfma_f32_16x16x32_bf16 v[34:37], v[154:157], v[206:209], 0
	v_mfma_f32_16x16x32_bf16 v[22:25], v[146:149], v[214:217], 0
	v_mfma_f32_16x16x32_bf16 v[18:21], v[154:157], v[214:217], 0
	v_mfma_f32_16x16x32_bf16 v[6:9], v[146:149], v[222:225], 0
	v_mfma_f32_16x16x32_bf16 v[2:5], v[154:157], v[222:225], 0
	v_mfma_f32_16x16x32_bf16 v[54:57], v[150:153], v[188:191], v[54:57]
	v_mfma_f32_16x16x32_bf16 v[50:53], v[158:161], v[188:191], v[50:53]
	v_mfma_f32_16x16x32_bf16 v[38:41], v[150:153], v[210:213], v[38:41]
	v_mfma_f32_16x16x32_bf16 v[34:37], v[158:161], v[210:213], v[34:37]
	v_mfma_f32_16x16x32_bf16 v[22:25], v[150:153], v[218:221], v[22:25]
	v_mfma_f32_16x16x32_bf16 v[18:21], v[158:161], v[218:221], v[18:21]
	v_mfma_f32_16x16x32_bf16 v[6:9], v[150:153], v[226:229], v[6:9]
	v_mfma_f32_16x16x32_bf16 v[2:5], v[158:161], v[226:229], v[2:5]
	s_setprio 0
	s_barrier
	s_add_i32 s0, 0, 0x18000
	s_add_i32 s27, 0, 0x1c000
	ds_read_b128 v[114:117], v254
	ds_read_b128 v[134:137], v254 offset:1024
	ds_read_b128 v[138:141], v254 offset:2048
	ds_read_b128 v[142:145], v254 offset:3072
	ds_read_b128 v[146:149], v255
	ds_read_b128 v[150:153], v255 offset:1024
	ds_read_b128 v[154:157], v255 offset:2048
	ds_read_b128 v[158:161], v255 offset:3072
	s_add_u32 s10, s10, 0x40000
	s_addc_u32 s11, s11, 0
	s_mov_b32 m0, s81
	ds_read_b128 v[184:187], v199 offset:32768
	ds_read_b128 v[188:191], v199 offset:33792
	ds_read_b128 v[206:209], v199 offset:34816
	ds_read_b128 v[210:213], v199 offset:35840
	ds_read_b128 v[214:217], v199 offset:36864
	ds_read_b128 v[218:221], v199 offset:37888
	ds_read_b128 v[222:225], v199 offset:38912
	global_load_lds_dwordx4 v162, s[10:11]
	s_mov_b32 m0, s82
	ds_read_b128 v[226:229], v199 offset:39936
	global_load_lds_dwordx4 v166, s[10:11]
	s_waitcnt vmcnt(8)
	s_waitcnt lgkmcnt(0)
	s_barrier
	s_setprio 1
	v_mfma_f32_16x16x32_bf16 v[130:133], v[114:117], v[184:187], v[130:133]
	v_mfma_f32_16x16x32_bf16 v[126:129], v[138:141], v[184:187], v[126:129]
	v_mfma_f32_16x16x32_bf16 v[110:113], v[114:117], v[206:209], v[110:113]
	v_mfma_f32_16x16x32_bf16 v[106:109], v[138:141], v[206:209], v[106:109]
	v_mfma_f32_16x16x32_bf16 v[94:97], v[114:117], v[214:217], v[94:97]
	v_mfma_f32_16x16x32_bf16 v[90:93], v[138:141], v[214:217], v[90:93]
	v_mfma_f32_16x16x32_bf16 v[78:81], v[114:117], v[222:225], v[78:81]
	v_mfma_f32_16x16x32_bf16 v[74:77], v[138:141], v[222:225], v[74:77]
	v_mfma_f32_16x16x32_bf16 v[130:133], v[134:137], v[188:191], v[130:133]
	v_mfma_f32_16x16x32_bf16 v[126:129], v[142:145], v[188:191], v[126:129]
	v_mfma_f32_16x16x32_bf16 v[110:113], v[134:137], v[210:213], v[110:113]
	v_mfma_f32_16x16x32_bf16 v[106:109], v[142:145], v[210:213], v[106:109]
	v_mfma_f32_16x16x32_bf16 v[94:97], v[134:137], v[218:221], v[94:97]
	v_mfma_f32_16x16x32_bf16 v[90:93], v[142:145], v[218:221], v[90:93]
	v_mfma_f32_16x16x32_bf16 v[78:81], v[134:137], v[226:229], v[78:81]
	v_mfma_f32_16x16x32_bf16 v[74:77], v[142:145], v[226:229], v[74:77]
	v_mfma_f32_16x16x32_bf16 v[122:125], v[146:149], v[184:187], v[122:125]
	v_mfma_f32_16x16x32_bf16 v[118:121], v[154:157], v[184:187], v[118:121]
	v_mfma_f32_16x16x32_bf16 v[102:105], v[146:149], v[206:209], v[102:105]
	v_mfma_f32_16x16x32_bf16 v[98:101], v[154:157], v[206:209], v[98:101]
	v_mfma_f32_16x16x32_bf16 v[86:89], v[146:149], v[214:217], v[86:89]
	v_mfma_f32_16x16x32_bf16 v[82:85], v[154:157], v[214:217], v[82:85]
	v_mfma_f32_16x16x32_bf16 v[70:73], v[146:149], v[222:225], v[70:73]
	v_mfma_f32_16x16x32_bf16 v[66:69], v[154:157], v[222:225], v[66:69]
	v_mfma_f32_16x16x32_bf16 v[122:125], v[150:153], v[188:191], v[122:125]
	v_mfma_f32_16x16x32_bf16 v[118:121], v[158:161], v[188:191], v[118:121]
	v_mfma_f32_16x16x32_bf16 v[102:105], v[150:153], v[210:213], v[102:105]
	v_mfma_f32_16x16x32_bf16 v[98:101], v[158:161], v[210:213], v[98:101]
	v_mfma_f32_16x16x32_bf16 v[86:89], v[150:153], v[218:221], v[86:89]
	v_mfma_f32_16x16x32_bf16 v[82:85], v[158:161], v[218:221], v[82:85]
	v_mfma_f32_16x16x32_bf16 v[70:73], v[150:153], v[226:229], v[70:73]
	v_mfma_f32_16x16x32_bf16 v[66:69], v[158:161], v[226:229], v[66:69]
	s_setprio 0
	s_barrier
	s_add_i32 s0, s0, s79
	s_mov_b32 m0, s0
	ds_read_b128 v[184:187], v199 offset:49152
	ds_read_b128 v[188:191], v199 offset:50176
	ds_read_b128 v[206:209], v199 offset:51200
	ds_read_b128 v[210:213], v199 offset:52224
	s_add_u32 s98, s8, 0x80
	s_addc_u32 s99, s9, 0
	global_load_lds_dwordx4 v164, s[98:99]
	s_add_i32 m0, s0, 0x2000
	s_add_u32 s8, s8, 0x40080
	s_addc_u32 s9, s9, 0
	s_add_i32 s0, s27, s79
	global_load_lds_dwordx4 v168, s[98:99]
	s_mov_b32 m0, s0
	ds_read_b128 v[214:217], v199 offset:53248
	global_load_lds_dwordx4 v164, s[8:9]
	s_add_i32 m0, s0, 0x2000
	ds_read_b128 v[218:221], v199 offset:54272
	global_load_lds_dwordx4 v168, s[8:9]
	s_add_u32 s98, s10, 0xfffc0080
	s_addc_u32 s99, s11, -1
	s_mov_b32 m0, s84
	ds_read_b128 v[222:225], v199 offset:55296
	global_load_lds_dwordx4 v162, s[98:99]
	s_mov_b32 m0, s85
	ds_read_b128 v[226:229], v199 offset:56320
	global_load_lds_dwordx4 v166, s[98:99]
	s_waitcnt vmcnt(8)
	s_waitcnt lgkmcnt(0)
	s_barrier
	s_setprio 1
	v_mfma_f32_16x16x32_bf16 v[62:65], v[114:117], v[184:187], v[62:65]
	v_mfma_f32_16x16x32_bf16 v[58:61], v[138:141], v[184:187], v[58:61]
	v_mfma_f32_16x16x32_bf16 v[46:49], v[114:117], v[206:209], v[46:49]
	v_mfma_f32_16x16x32_bf16 v[42:45], v[138:141], v[206:209], v[42:45]
	v_mfma_f32_16x16x32_bf16 v[30:33], v[114:117], v[214:217], v[30:33]
	v_mfma_f32_16x16x32_bf16 v[26:29], v[138:141], v[214:217], v[26:29]
	v_mfma_f32_16x16x32_bf16 v[14:17], v[114:117], v[222:225], v[14:17]
	v_mfma_f32_16x16x32_bf16 v[10:13], v[138:141], v[222:225], v[10:13]
	v_mfma_f32_16x16x32_bf16 v[62:65], v[134:137], v[188:191], v[62:65]
	v_mfma_f32_16x16x32_bf16 v[58:61], v[142:145], v[188:191], v[58:61]
	v_mfma_f32_16x16x32_bf16 v[46:49], v[134:137], v[210:213], v[46:49]
	v_mfma_f32_16x16x32_bf16 v[42:45], v[142:145], v[210:213], v[42:45]
	v_mfma_f32_16x16x32_bf16 v[30:33], v[134:137], v[218:221], v[30:33]
	v_mfma_f32_16x16x32_bf16 v[26:29], v[142:145], v[218:221], v[26:29]
	v_mfma_f32_16x16x32_bf16 v[14:17], v[134:137], v[226:229], v[14:17]
	v_mfma_f32_16x16x32_bf16 v[10:13], v[142:145], v[226:229], v[10:13]
	v_mfma_f32_16x16x32_bf16 v[54:57], v[146:149], v[184:187], v[54:57]
	v_mfma_f32_16x16x32_bf16 v[50:53], v[154:157], v[184:187], v[50:53]
	v_mfma_f32_16x16x32_bf16 v[38:41], v[146:149], v[206:209], v[38:41]
	v_mfma_f32_16x16x32_bf16 v[34:37], v[154:157], v[206:209], v[34:37]
	v_mfma_f32_16x16x32_bf16 v[22:25], v[146:149], v[214:217], v[22:25]
	v_mfma_f32_16x16x32_bf16 v[18:21], v[154:157], v[214:217], v[18:21]
	v_mfma_f32_16x16x32_bf16 v[6:9], v[146:149], v[222:225], v[6:9]
	v_mfma_f32_16x16x32_bf16 v[2:5], v[154:157], v[222:225], v[2:5]
	v_mfma_f32_16x16x32_bf16 v[54:57], v[150:153], v[188:191], v[54:57]
	v_mfma_f32_16x16x32_bf16 v[50:53], v[158:161], v[188:191], v[50:53]
	v_mfma_f32_16x16x32_bf16 v[38:41], v[150:153], v[210:213], v[38:41]
	v_mfma_f32_16x16x32_bf16 v[34:37], v[158:161], v[210:213], v[34:37]
	v_mfma_f32_16x16x32_bf16 v[22:25], v[150:153], v[218:221], v[22:25]
	v_mfma_f32_16x16x32_bf16 v[18:21], v[158:161], v[218:221], v[18:21]
	v_mfma_f32_16x16x32_bf16 v[6:9], v[150:153], v[226:229], v[6:9]
	v_mfma_f32_16x16x32_bf16 v[2:5], v[158:161], v[226:229], v[2:5]
	s_setprio 0
	s_barrier
	s_add_i32 s26, s26, 2
	s_add_u32 s6, s6, 0x100
	s_addc_u32 s7, s7, 0
	s_add_u32 s24, s24, 0x100
	s_addc_u32 s25, s25, 0
	s_cmp_gt_u32 s26, 13
	s_cbranch_scc1 .Lpeel_x1
.LBB0_368:
	ds_read_b128 v[114:117], v197
	ds_read_b128 v[134:137], v197 offset:1024
	ds_read_b128 v[138:141], v197 offset:2048
	ds_read_b128 v[142:145], v197 offset:3072
	ds_read_b128 v[146:149], v198
	ds_read_b128 v[150:153], v198 offset:1024
	ds_read_b128 v[154:157], v198 offset:2048
	ds_read_b128 v[158:161], v198 offset:3072
	s_add_u32 s0, s6, 0xfffc0080
	s_addc_u32 s8, s7, -1
	s_cmp_eq_u32 s26, 12
	s_cselect_b32 s11, s2, s8
	s_cselect_b32 s10, s3, s0
	s_cselect_b32 s9, s12, s25
	s_cselect_b32 s8, s13, s24
	s_add_i32 m0, s31, 0xc000
	ds_read_b128 v[184:187], v199
	ds_read_b128 v[188:191], v199 offset:1024
	ds_read_b128 v[206:209], v199 offset:2048
	ds_read_b128 v[210:213], v199 offset:3072
	ds_read_b128 v[214:217], v199 offset:4096
	ds_read_b128 v[218:221], v199 offset:5120
	ds_read_b128 v[222:225], v199 offset:6144
	global_load_lds_dwordx4 v180, s[6:7]
	s_add_i32 m0, s31, 0xe000
	ds_read_b128 v[226:229], v199 offset:7168
	global_load_lds_dwordx4 v182, s[6:7]
	s_waitcnt vmcnt(8)
	s_waitcnt lgkmcnt(0)
	s_barrier
	s_setprio 1
	v_mfma_f32_16x16x32_bf16 v[130:133], v[114:117], v[184:187], v[130:133]
	v_mfma_f32_16x16x32_bf16 v[126:129], v[138:141], v[184:187], v[126:129]
	v_mfma_f32_16x16x32_bf16 v[110:113], v[114:117], v[206:209], v[110:113]
	v_mfma_f32_16x16x32_bf16 v[106:109], v[138:141], v[206:209], v[106:109]
	v_mfma_f32_16x16x32_bf16 v[94:97], v[114:117], v[214:217], v[94:97]
	v_mfma_f32_16x16x32_bf16 v[90:93], v[138:141], v[214:217], v[90:93]
	v_mfma_f32_16x16x32_bf16 v[78:81], v[114:117], v[222:225], v[78:81]
	v_mfma_f32_16x16x32_bf16 v[74:77], v[138:141], v[222:225], v[74:77]
	v_mfma_f32_16x16x32_bf16 v[130:133], v[134:137], v[188:191], v[130:133]
	v_mfma_f32_16x16x32_bf16 v[126:129], v[142:145], v[188:191], v[126:129]
	v_mfma_f32_16x16x32_bf16 v[110:113], v[134:137], v[210:213], v[110:113]
	v_mfma_f32_16x16x32_bf16 v[106:109], v[142:145], v[210:213], v[106:109]
	v_mfma_f32_16x16x32_bf16 v[94:97], v[134:137], v[218:221], v[94:97]
	v_mfma_f32_16x16x32_bf16 v[90:93], v[142:145], v[218:221], v[90:93]
	v_mfma_f32_16x16x32_bf16 v[78:81], v[134:137], v[226:229], v[78:81]
	v_mfma_f32_16x16x32_bf16 v[74:77], v[142:145], v[226:229], v[74:77]
	v_mfma_f32_16x16x32_bf16 v[122:125], v[146:149], v[184:187], v[122:125]
	v_mfma_f32_16x16x32_bf16 v[118:121], v[154:157], v[184:187], v[118:121]
	v_mfma_f32_16x16x32_bf16 v[102:105], v[146:149], v[206:209], v[102:105]
	v_mfma_f32_16x16x32_bf16 v[98:101], v[154:157], v[206:209], v[98:101]
	v_mfma_f32_16x16x32_bf16 v[86:89], v[146:149], v[214:217], v[86:89]
	v_mfma_f32_16x16x32_bf16 v[82:85], v[154:157], v[214:217], v[82:85]
	v_mfma_f32_16x16x32_bf16 v[70:73], v[146:149], v[222:225], v[70:73]
	v_mfma_f32_16x16x32_bf16 v[66:69], v[154:157], v[222:225], v[66:69]
	v_mfma_f32_16x16x32_bf16 v[122:125], v[150:153], v[188:191], v[122:125]
	v_mfma_f32_16x16x32_bf16 v[118:121], v[158:161], v[188:191], v[118:121]
	v_mfma_f32_16x16x32_bf16 v[102:105], v[150:153], v[210:213], v[102:105]
	v_mfma_f32_16x16x32_bf16 v[98:101], v[158:161], v[210:213], v[98:101]
	v_mfma_f32_16x16x32_bf16 v[86:89], v[150:153], v[218:221], v[86:89]
	v_mfma_f32_16x16x32_bf16 v[82:85], v[158:161], v[218:221], v[82:85]
	v_mfma_f32_16x16x32_bf16 v[70:73], v[150:153], v[226:229], v[70:73]
	v_mfma_f32_16x16x32_bf16 v[66:69], v[158:161], v[226:229], v[66:69]
	s_setprio 0
	s_barrier
	s_add_i32 s0, s89, s79
	s_mov_b32 m0, s0
	ds_read_b128 v[184:187], v199 offset:16384
	ds_read_b128 v[188:191], v199 offset:17408
	ds_read_b128 v[206:209], v199 offset:18432
	ds_read_b128 v[210:213], v199 offset:19456
	global_load_lds_dwordx4 v164, s[8:9]
	s_add_i32 m0, s0, 0x2000
	s_add_u32 s62, s8, 0x40000
	s_addc_u32 s63, s9, 0
	s_add_i32 s0, s90, s79
	global_load_lds_dwordx4 v168, s[8:9]
	s_mov_b32 m0, s0
	ds_read_b128 v[214:217], v199 offset:20480
	global_load_lds_dwordx4 v164, s[62:63]
	s_add_i32 m0, s0, 0x2000
	ds_read_b128 v[218:221], v199 offset:21504
	global_load_lds_dwordx4 v168, s[62:63]
	s_mov_b32 m0, s31
	ds_read_b128 v[222:225], v199 offset:22528
	global_load_lds_dwordx4 v162, s[10:11]
	s_mov_b32 m0, s80
	ds_read_b128 v[226:229], v199 offset:23552
	global_load_lds_dwordx4 v166, s[10:11]
	s_waitcnt vmcnt(8)
	s_waitcnt lgkmcnt(0)
	s_barrier
	s_setprio 1
	v_mfma_f32_16x16x32_bf16 v[62:65], v[114:117], v[184:187], v[62:65]
	v_mfma_f32_16x16x32_bf16 v[58:61], v[138:141], v[184:187], v[58:61]
	v_mfma_f32_16x16x32_bf16 v[46:49], v[114:117], v[206:209], v[46:49]
	v_mfma_f32_16x16x32_bf16 v[42:45], v[138:141], v[206:209], v[42:45]
	v_mfma_f32_16x16x32_bf16 v[30:33], v[114:117], v[214:217], v[30:33]
	v_mfma_f32_16x16x32_bf16 v[26:29], v[138:141], v[214:217], v[26:29]
	v_mfma_f32_16x16x32_bf16 v[14:17], v[114:117], v[222:225], v[14:17]
	v_mfma_f32_16x16x32_bf16 v[10:13], v[138:141], v[222:225], v[10:13]
	v_mfma_f32_16x16x32_bf16 v[62:65], v[134:137], v[188:191], v[62:65]
	v_mfma_f32_16x16x32_bf16 v[58:61], v[142:145], v[188:191], v[58:61]
	v_mfma_f32_16x16x32_bf16 v[46:49], v[134:137], v[210:213], v[46:49]
	v_mfma_f32_16x16x32_bf16 v[42:45], v[142:145], v[210:213], v[42:45]
	v_mfma_f32_16x16x32_bf16 v[30:33], v[134:137], v[218:221], v[30:33]
	v_mfma_f32_16x16x32_bf16 v[26:29], v[142:145], v[218:221], v[26:29]
	v_mfma_f32_16x16x32_bf16 v[14:17], v[134:137], v[226:229], v[14:17]
	v_mfma_f32_16x16x32_bf16 v[10:13], v[142:145], v[226:229], v[10:13]
	v_mfma_f32_16x16x32_bf16 v[54:57], v[146:149], v[184:187], v[54:57]
	v_mfma_f32_16x16x32_bf16 v[50:53], v[154:157], v[184:187], v[50:53]
	v_mfma_f32_16x16x32_bf16 v[38:41], v[146:149], v[206:209], v[38:41]
	v_mfma_f32_16x16x32_bf16 v[34:37], v[154:157], v[206:209], v[34:37]
	v_mfma_f32_16x16x32_bf16 v[22:25], v[146:149], v[214:217], v[22:25]
	v_mfma_f32_16x16x32_bf16 v[18:21], v[154:157], v[214:217], v[18:21]
	v_mfma_f32_16x16x32_bf16 v[6:9], v[146:149], v[222:225], v[6:9]
	v_mfma_f32_16x16x32_bf16 v[2:5], v[154:157], v[222:225], v[2:5]
	v_mfma_f32_16x16x32_bf16 v[54:57], v[150:153], v[188:191], v[54:57]
	v_mfma_f32_16x16x32_bf16 v[50:53], v[158:161], v[188:191], v[50:53]
	v_mfma_f32_16x16x32_bf16 v[38:41], v[150:153], v[210:213], v[38:41]
	v_mfma_f32_16x16x32_bf16 v[34:37], v[158:161], v[210:213], v[34:37]
	v_mfma_f32_16x16x32_bf16 v[22:25], v[150:153], v[218:221], v[22:25]
	v_mfma_f32_16x16x32_bf16 v[18:21], v[158:161], v[218:221], v[18:21]
	v_mfma_f32_16x16x32_bf16 v[6:9], v[150:153], v[226:229], v[6:9]
	v_mfma_f32_16x16x32_bf16 v[2:5], v[158:161], v[226:229], v[2:5]
	s_setprio 0
	s_barrier
	s_add_i32 s0, 0, 0x18000
	s_add_i32 s27, 0, 0x1c000
	ds_read_b128 v[114:117], v254
	ds_read_b128 v[134:137], v254 offset:1024
	ds_read_b128 v[138:141], v254 offset:2048
	ds_read_b128 v[142:145], v254 offset:3072
	ds_read_b128 v[146:149], v255
	ds_read_b128 v[150:153], v255 offset:1024
	ds_read_b128 v[154:157], v255 offset:2048
	ds_read_b128 v[158:161], v255 offset:3072
	s_add_u32 s10, s10, 0x40000
	s_addc_u32 s11, s11, 0
	s_mov_b32 m0, s81
	ds_read_b128 v[184:187], v199 offset:32768
	ds_read_b128 v[188:191], v199 offset:33792
	ds_read_b128 v[206:209], v199 offset:34816
	ds_read_b128 v[210:213], v199 offset:35840
	ds_read_b128 v[214:217], v199 offset:36864
	ds_read_b128 v[218:221], v199 offset:37888
	ds_read_b128 v[222:225], v199 offset:38912
	global_load_lds_dwordx4 v162, s[10:11]
	s_mov_b32 m0, s82
	ds_read_b128 v[226:229], v199 offset:39936
	global_load_lds_dwordx4 v166, s[10:11]
	s_waitcnt vmcnt(8)
	s_waitcnt lgkmcnt(0)
	s_barrier
	s_setprio 1
	v_mfma_f32_16x16x32_bf16 v[130:133], v[114:117], v[184:187], v[130:133]
	v_mfma_f32_16x16x32_bf16 v[126:129], v[138:141], v[184:187], v[126:129]
	v_mfma_f32_16x16x32_bf16 v[110:113], v[114:117], v[206:209], v[110:113]
	v_mfma_f32_16x16x32_bf16 v[106:109], v[138:141], v[206:209], v[106:109]
	v_mfma_f32_16x16x32_bf16 v[94:97], v[114:117], v[214:217], v[94:97]
	v_mfma_f32_16x16x32_bf16 v[90:93], v[138:141], v[214:217], v[90:93]
	v_mfma_f32_16x16x32_bf16 v[78:81], v[114:117], v[222:225], v[78:81]
	v_mfma_f32_16x16x32_bf16 v[74:77], v[138:141], v[222:225], v[74:77]
	v_mfma_f32_16x16x32_bf16 v[130:133], v[134:137], v[188:191], v[130:133]
	v_mfma_f32_16x16x32_bf16 v[126:129], v[142:145], v[188:191], v[126:129]
	v_mfma_f32_16x16x32_bf16 v[110:113], v[134:137], v[210:213], v[110:113]
	v_mfma_f32_16x16x32_bf16 v[106:109], v[142:145], v[210:213], v[106:109]
	v_mfma_f32_16x16x32_bf16 v[94:97], v[134:137], v[218:221], v[94:97]
	v_mfma_f32_16x16x32_bf16 v[90:93], v[142:145], v[218:221], v[90:93]
	v_mfma_f32_16x16x32_bf16 v[78:81], v[134:137], v[226:229], v[78:81]
	v_mfma_f32_16x16x32_bf16 v[74:77], v[142:145], v[226:229], v[74:77]
	v_mfma_f32_16x16x32_bf16 v[122:125], v[146:149], v[184:187], v[122:125]
	v_mfma_f32_16x16x32_bf16 v[118:121], v[154:157], v[184:187], v[118:121]
	v_mfma_f32_16x16x32_bf16 v[102:105], v[146:149], v[206:209], v[102:105]
	v_mfma_f32_16x16x32_bf16 v[98:101], v[154:157], v[206:209], v[98:101]
	v_mfma_f32_16x16x32_bf16 v[86:89], v[146:149], v[214:217], v[86:89]
	v_mfma_f32_16x16x32_bf16 v[82:85], v[154:157], v[214:217], v[82:85]
	v_mfma_f32_16x16x32_bf16 v[70:73], v[146:149], v[222:225], v[70:73]
	v_mfma_f32_16x16x32_bf16 v[66:69], v[154:157], v[222:225], v[66:69]
	v_mfma_f32_16x16x32_bf16 v[122:125], v[150:153], v[188:191], v[122:125]
	v_mfma_f32_16x16x32_bf16 v[118:121], v[158:161], v[188:191], v[118:121]
	v_mfma_f32_16x16x32_bf16 v[102:105], v[150:153], v[210:213], v[102:105]
	v_mfma_f32_16x16x32_bf16 v[98:101], v[158:161], v[210:213], v[98:101]
	v_mfma_f32_16x16x32_bf16 v[86:89], v[150:153], v[218:221], v[86:89]
	v_mfma_f32_16x16x32_bf16 v[82:85], v[158:161], v[218:221], v[82:85]
	v_mfma_f32_16x16x32_bf16 v[70:73], v[150:153], v[226:229], v[70:73]
	v_mfma_f32_16x16x32_bf16 v[66:69], v[158:161], v[226:229], v[66:69]
	s_setprio 0
	s_barrier
	s_add_i32 s0, s0, s79
	s_mov_b32 m0, s0
	ds_read_b128 v[184:187], v199 offset:49152
	ds_read_b128 v[188:191], v199 offset:50176
	ds_read_b128 v[206:209], v199 offset:51200
	ds_read_b128 v[210:213], v199 offset:52224
	s_add_u32 s98, s8, 0x80
	s_addc_u32 s99, s9, 0
	global_load_lds_dwordx4 v164, s[98:99]
	s_add_i32 m0, s0, 0x2000
	s_add_u32 s8, s8, 0x40080
	s_addc_u32 s9, s9, 0
	s_add_i32 s0, s27, s79
	global_load_lds_dwordx4 v168, s[98:99]
	s_mov_b32 m0, s0
	ds_read_b128 v[214:217], v199 offset:53248
	global_load_lds_dwordx4 v164, s[8:9]
	s_add_i32 m0, s0, 0x2000
	ds_read_b128 v[218:221], v199 offset:54272
	global_load_lds_dwordx4 v168, s[8:9]
	s_add_u32 s98, s10, 0xfffc0080
	s_addc_u32 s99, s11, -1
	s_mov_b32 m0, s84
	ds_read_b128 v[222:225], v199 offset:55296
	global_load_lds_dwordx4 v162, s[98:99]
	s_mov_b32 m0, s85
	ds_read_b128 v[226:229], v199 offset:56320
	global_load_lds_dwordx4 v166, s[98:99]
	s_waitcnt vmcnt(8)
	s_waitcnt lgkmcnt(0)
	s_barrier
	s_setprio 1
	v_mfma_f32_16x16x32_bf16 v[62:65], v[114:117], v[184:187], v[62:65]
	v_mfma_f32_16x16x32_bf16 v[58:61], v[138:141], v[184:187], v[58:61]
	v_mfma_f32_16x16x32_bf16 v[46:49], v[114:117], v[206:209], v[46:49]
	v_mfma_f32_16x16x32_bf16 v[42:45], v[138:141], v[206:209], v[42:45]
	v_mfma_f32_16x16x32_bf16 v[30:33], v[114:117], v[214:217], v[30:33]
	v_mfma_f32_16x16x32_bf16 v[26:29], v[138:141], v[214:217], v[26:29]
	v_mfma_f32_16x16x32_bf16 v[14:17], v[114:117], v[222:225], v[14:17]
	v_mfma_f32_16x16x32_bf16 v[10:13], v[138:141], v[222:225], v[10:13]
	v_mfma_f32_16x16x32_bf16 v[62:65], v[134:137], v[188:191], v[62:65]
	v_mfma_f32_16x16x32_bf16 v[58:61], v[142:145], v[188:191], v[58:61]
	v_mfma_f32_16x16x32_bf16 v[46:49], v[134:137], v[210:213], v[46:49]
	v_mfma_f32_16x16x32_bf16 v[42:45], v[142:145], v[210:213], v[42:45]
	v_mfma_f32_16x16x32_bf16 v[30:33], v[134:137], v[218:221], v[30:33]
	v_mfma_f32_16x16x32_bf16 v[26:29], v[142:145], v[218:221], v[26:29]
	v_mfma_f32_16x16x32_bf16 v[14:17], v[134:137], v[226:229], v[14:17]
	v_mfma_f32_16x16x32_bf16 v[10:13], v[142:145], v[226:229], v[10:13]
	v_mfma_f32_16x16x32_bf16 v[54:57], v[146:149], v[184:187], v[54:57]
	v_mfma_f32_16x16x32_bf16 v[50:53], v[154:157], v[184:187], v[50:53]
	v_mfma_f32_16x16x32_bf16 v[38:41], v[146:149], v[206:209], v[38:41]
	v_mfma_f32_16x16x32_bf16 v[34:37], v[154:157], v[206:209], v[34:37]
	v_mfma_f32_16x16x32_bf16 v[22:25], v[146:149], v[214:217], v[22:25]
	v_mfma_f32_16x16x32_bf16 v[18:21], v[154:157], v[214:217], v[18:21]
	v_mfma_f32_16x16x32_bf16 v[6:9], v[146:149], v[222:225], v[6:9]
	v_mfma_f32_16x16x32_bf16 v[2:5], v[154:157], v[222:225], v[2:5]
	v_mfma_f32_16x16x32_bf16 v[54:57], v[150:153], v[188:191], v[54:57]
	v_mfma_f32_16x16x32_bf16 v[50:53], v[158:161], v[188:191], v[50:53]
	v_mfma_f32_16x16x32_bf16 v[38:41], v[150:153], v[210:213], v[38:41]
	v_mfma_f32_16x16x32_bf16 v[34:37], v[158:161], v[210:213], v[34:37]
	v_mfma_f32_16x16x32_bf16 v[22:25], v[150:153], v[218:221], v[22:25]
	v_mfma_f32_16x16x32_bf16 v[18:21], v[158:161], v[218:221], v[18:21]
	v_mfma_f32_16x16x32_bf16 v[6:9], v[150:153], v[226:229], v[6:9]
	v_mfma_f32_16x16x32_bf16 v[2:5], v[158:161], v[226:229], v[2:5]
	s_setprio 0
	s_barrier
	s_add_i32 s26, s26, 2
	s_add_u32 s6, s6, 0x100
	s_addc_u32 s7, s7, 0
	s_add_u32 s24, s24, 0x100
	s_addc_u32 s25, s25, 0
	s_cmp_gt_u32 s26, 13
	s_cbranch_scc0 .LBB0_368

.LBB0_990:
	s_ashr_i32 s37, s36, 31
	s_lshl_b64 s[2:3], s[36:37], 19
	s_add_u32 s40, s48, s2
	s_addc_u32 s41, s49, s3
	s_and_b64 s[2:3], s[44:45], exec
	s_cselect_b32 s1, s41, s9
	s_cselect_b32 s2, s40, s8
	s_ashr_i32 s39, s38, 31
	s_lshl_b64 s[4:5], s[38:39], 19
	s_add_u32 s42, s50, s4
	s_addc_u32 s43, s51, s5
	s_and_b64 s[4:5], s[44:45], exec
	s_cselect_b32 s3, s43, s11
	s_cselect_b32 s4, s42, s10
	s_add_u32 s8, s8, 0x40080
	s_addc_u32 s9, s9, 0
	s_add_u32 s5, s10, 0x100
	s_addc_u32 s7, s11, 0
	s_mov_b32 s22, -2
	v_add_u32_e32 v254, 0x18000, v213
	v_add_u32_e32 v255, 0x1c000, v213
	ds_read_b128 v[66:69], v219
	ds_read_b128 v[70:73], v219 offset:1024
	ds_read_b128 v[86:89], v219 offset:2048
	ds_read_b128 v[106:109], v219 offset:3072
	ds_read_b128 v[146:149], v220
	ds_read_b128 v[150:153], v220 offset:1024
	ds_read_b128 v[154:157], v220 offset:2048
	ds_read_b128 v[158:161], v220 offset:3072
	s_add_u32 s10, s8, 0xfffc0080
	s_addc_u32 s11, s9, -1
	s_cmp_eq_u32 s22, 12
	s_cselect_b32 s45, s1, s11
	s_cselect_b32 s44, s2, s10
	s_cselect_b32 s11, s3, s7
	s_cselect_b32 s10, s4, s5
	s_add_i32 m0, s54, 0xc000
	ds_read_b128 v[162:165], v221
	ds_read_b128 v[166:169], v221 offset:1024
	ds_read_b128 v[170:173], v221 offset:2048
	ds_read_b128 v[174:177], v221 offset:3072
	ds_read_b128 v[196:199], v221 offset:4096
	ds_read_b128 v[200:203], v221 offset:5120
	ds_read_b128 v[204:207], v221 offset:6144
	global_load_lds_dwordx4 v192, s[8:9]
	s_add_i32 m0, s54, 0xe000
	ds_read_b128 v[208:211], v221 offset:7168
	global_load_lds_dwordx4 v194, s[8:9]
	s_waitcnt vmcnt(8)
	s_waitcnt lgkmcnt(0)
	s_barrier
	s_setprio 1
	v_mfma_f32_16x16x32_bf16 v[142:145], v[66:69], v[162:165], 0
	v_mfma_f32_16x16x32_bf16 v[134:137], v[86:89], v[162:165], 0
	v_mfma_f32_16x16x32_bf16 v[126:129], v[66:69], v[170:173], 0
	v_mfma_f32_16x16x32_bf16 v[122:125], v[86:89], v[170:173], 0
	v_mfma_f32_16x16x32_bf16 v[110:113], v[66:69], v[196:199], 0
	v_mfma_f32_16x16x32_bf16 v[102:105], v[86:89], v[196:199], 0
	v_mfma_f32_16x16x32_bf16 v[90:93], v[66:69], v[204:207], 0
	v_mfma_f32_16x16x32_bf16 v[82:85], v[86:89], v[204:207], 0
	v_mfma_f32_16x16x32_bf16 v[142:145], v[70:73], v[166:169], v[142:145]
	v_mfma_f32_16x16x32_bf16 v[134:137], v[106:109], v[166:169], v[134:137]
	v_mfma_f32_16x16x32_bf16 v[126:129], v[70:73], v[174:177], v[126:129]
	v_mfma_f32_16x16x32_bf16 v[122:125], v[106:109], v[174:177], v[122:125]
	v_mfma_f32_16x16x32_bf16 v[110:113], v[70:73], v[200:203], v[110:113]
	v_mfma_f32_16x16x32_bf16 v[102:105], v[106:109], v[200:203], v[102:105]
	v_mfma_f32_16x16x32_bf16 v[90:93], v[70:73], v[208:211], v[90:93]
	v_mfma_f32_16x16x32_bf16 v[82:85], v[106:109], v[208:211], v[82:85]
	v_mfma_f32_16x16x32_bf16 v[138:141], v[146:149], v[162:165], 0
	v_mfma_f32_16x16x32_bf16 v[130:133], v[154:157], v[162:165], 0
	v_mfma_f32_16x16x32_bf16 v[118:121], v[146:149], v[170:173], 0
	v_mfma_f32_16x16x32_bf16 v[114:117], v[154:157], v[170:173], 0
	v_mfma_f32_16x16x32_bf16 v[98:101], v[146:149], v[196:199], 0
	v_mfma_f32_16x16x32_bf16 v[94:97], v[154:157], v[196:199], 0
	v_mfma_f32_16x16x32_bf16 v[78:81], v[146:149], v[204:207], 0
	v_mfma_f32_16x16x32_bf16 v[74:77], v[154:157], v[204:207], 0
	v_mfma_f32_16x16x32_bf16 v[138:141], v[150:153], v[166:169], v[138:141]
	v_mfma_f32_16x16x32_bf16 v[130:133], v[158:161], v[166:169], v[130:133]
	v_mfma_f32_16x16x32_bf16 v[118:121], v[150:153], v[174:177], v[118:121]
	v_mfma_f32_16x16x32_bf16 v[114:117], v[158:161], v[174:177], v[114:117]
	v_mfma_f32_16x16x32_bf16 v[98:101], v[150:153], v[200:203], v[98:101]
	v_mfma_f32_16x16x32_bf16 v[94:97], v[158:161], v[200:203], v[94:97]
	v_mfma_f32_16x16x32_bf16 v[78:81], v[150:153], v[208:211], v[78:81]
	v_mfma_f32_16x16x32_bf16 v[74:77], v[158:161], v[208:211], v[74:77]
	s_setprio 0
	s_barrier
	s_add_i32 s37, s62, s53
	s_mov_b32 m0, s37
	ds_read_b128 v[162:165], v221 offset:16384
	ds_read_b128 v[166:169], v221 offset:17408
	ds_read_b128 v[170:173], v221 offset:18432
	ds_read_b128 v[174:177], v221 offset:19456
	global_load_lds_dwordx4 v184, s[10:11]
	s_add_i32 m0, s37, 0x2000
	s_add_u32 s46, s10, 0x40000
	s_addc_u32 s47, s11, 0
	s_add_i32 s37, s63, s53
	global_load_lds_dwordx4 v188, s[10:11]
	s_mov_b32 m0, s37
	ds_read_b128 v[196:199], v221 offset:20480
	global_load_lds_dwordx4 v184, s[46:47]
	s_add_i32 m0, s37, 0x2000
	ds_read_b128 v[200:203], v221 offset:21504
	global_load_lds_dwordx4 v188, s[46:47]
	s_mov_b32 m0, s54
	ds_read_b128 v[204:207], v221 offset:22528
	global_load_lds_dwordx4 v182, s[44:45]
	s_mov_b32 m0, s55
	ds_read_b128 v[208:211], v221 offset:23552
	global_load_lds_dwordx4 v186, s[44:45]
	s_waitcnt vmcnt(8)
	s_waitcnt lgkmcnt(0)
	s_barrier
	s_setprio 1
	v_mfma_f32_16x16x32_bf16 v[62:65], v[66:69], v[162:165], 0
	v_mfma_f32_16x16x32_bf16 v[54:57], v[86:89], v[162:165], 0
	v_mfma_f32_16x16x32_bf16 v[46:49], v[66:69], v[170:173], 0
	v_mfma_f32_16x16x32_bf16 v[42:45], v[86:89], v[170:173], 0
	v_mfma_f32_16x16x32_bf16 v[30:33], v[66:69], v[196:199], 0
	v_mfma_f32_16x16x32_bf16 v[26:29], v[86:89], v[196:199], 0
	v_mfma_f32_16x16x32_bf16 v[14:17], v[66:69], v[204:207], 0
	v_mfma_f32_16x16x32_bf16 v[10:13], v[86:89], v[204:207], 0
	v_mfma_f32_16x16x32_bf16 v[62:65], v[70:73], v[166:169], v[62:65]
	v_mfma_f32_16x16x32_bf16 v[54:57], v[106:109], v[166:169], v[54:57]
	v_mfma_f32_16x16x32_bf16 v[46:49], v[70:73], v[174:177], v[46:49]
	v_mfma_f32_16x16x32_bf16 v[42:45], v[106:109], v[174:177], v[42:45]
	v_mfma_f32_16x16x32_bf16 v[30:33], v[70:73], v[200:203], v[30:33]
	v_mfma_f32_16x16x32_bf16 v[26:29], v[106:109], v[200:203], v[26:29]
	v_mfma_f32_16x16x32_bf16 v[14:17], v[70:73], v[208:211], v[14:17]
	v_mfma_f32_16x16x32_bf16 v[10:13], v[106:109], v[208:211], v[10:13]
	v_mfma_f32_16x16x32_bf16 v[58:61], v[146:149], v[162:165], 0
	v_mfma_f32_16x16x32_bf16 v[50:53], v[154:157], v[162:165], 0
	v_mfma_f32_16x16x32_bf16 v[38:41], v[146:149], v[170:173], 0
	v_mfma_f32_16x16x32_bf16 v[34:37], v[154:157], v[170:173], 0
	v_mfma_f32_16x16x32_bf16 v[22:25], v[146:149], v[196:199], 0
	v_mfma_f32_16x16x32_bf16 v[18:21], v[154:157], v[196:199], 0
	v_mfma_f32_16x16x32_bf16 v[6:9], v[146:149], v[204:207], 0
	v_mfma_f32_16x16x32_bf16 v[2:5], v[154:157], v[204:207], 0
	v_mfma_f32_16x16x32_bf16 v[58:61], v[150:153], v[166:169], v[58:61]
	v_mfma_f32_16x16x32_bf16 v[50:53], v[158:161], v[166:169], v[50:53]
	v_mfma_f32_16x16x32_bf16 v[38:41], v[150:153], v[174:177], v[38:41]
	v_mfma_f32_16x16x32_bf16 v[34:37], v[158:161], v[174:177], v[34:37]
	v_mfma_f32_16x16x32_bf16 v[22:25], v[150:153], v[200:203], v[22:25]
	v_mfma_f32_16x16x32_bf16 v[18:21], v[158:161], v[200:203], v[18:21]
	v_mfma_f32_16x16x32_bf16 v[6:9], v[150:153], v[208:211], v[6:9]
	v_mfma_f32_16x16x32_bf16 v[2:5], v[158:161], v[208:211], v[2:5]
	s_setprio 0
	s_barrier
	s_add_i32 s37, 0, 0x18000
	s_add_i32 s39, 0, 0x1c000
	ds_read_b128 v[66:69], v254
	ds_read_b128 v[70:73], v254 offset:1024
	ds_read_b128 v[86:89], v254 offset:2048
	ds_read_b128 v[106:109], v254 offset:3072
	ds_read_b128 v[146:149], v255
	ds_read_b128 v[150:153], v255 offset:1024
	ds_read_b128 v[154:157], v255 offset:2048
	ds_read_b128 v[158:161], v255 offset:3072
	s_add_u32 s44, s44, 0x40000
	s_addc_u32 s45, s45, 0
	s_mov_b32 m0, s56
	ds_read_b128 v[162:165], v221 offset:32768
	ds_read_b128 v[166:169], v221 offset:33792
	ds_read_b128 v[170:173], v221 offset:34816
	ds_read_b128 v[174:177], v221 offset:35840
	ds_read_b128 v[196:199], v221 offset:36864
	ds_read_b128 v[200:203], v221 offset:37888
	ds_read_b128 v[204:207], v221 offset:38912
	global_load_lds_dwordx4 v182, s[44:45]
	s_mov_b32 m0, s57
	ds_read_b128 v[208:211], v221 offset:39936
	global_load_lds_dwordx4 v186, s[44:45]
	s_waitcnt vmcnt(8)
	s_waitcnt lgkmcnt(0)
	s_barrier
	s_setprio 1
	v_mfma_f32_16x16x32_bf16 v[142:145], v[66:69], v[162:165], v[142:145]
	v_mfma_f32_16x16x32_bf16 v[134:137], v[86:89], v[162:165], v[134:137]
	v_mfma_f32_16x16x32_bf16 v[126:129], v[66:69], v[170:173], v[126:129]
	v_mfma_f32_16x16x32_bf16 v[122:125], v[86:89], v[170:173], v[122:125]
	v_mfma_f32_16x16x32_bf16 v[110:113], v[66:69], v[196:199], v[110:113]
	v_mfma_f32_16x16x32_bf16 v[102:105], v[86:89], v[196:199], v[102:105]
	v_mfma_f32_16x16x32_bf16 v[90:93], v[66:69], v[204:207], v[90:93]
	v_mfma_f32_16x16x32_bf16 v[82:85], v[86:89], v[204:207], v[82:85]
	v_mfma_f32_16x16x32_bf16 v[142:145], v[70:73], v[166:169], v[142:145]
	v_mfma_f32_16x16x32_bf16 v[134:137], v[106:109], v[166:169], v[134:137]
	v_mfma_f32_16x16x32_bf16 v[126:129], v[70:73], v[174:177], v[126:129]
	v_mfma_f32_16x16x32_bf16 v[122:125], v[106:109], v[174:177], v[122:125]
	v_mfma_f32_16x16x32_bf16 v[110:113], v[70:73], v[200:203], v[110:113]
	v_mfma_f32_16x16x32_bf16 v[102:105], v[106:109], v[200:203], v[102:105]
	v_mfma_f32_16x16x32_bf16 v[90:93], v[70:73], v[208:211], v[90:93]
	v_mfma_f32_16x16x32_bf16 v[82:85], v[106:109], v[208:211], v[82:85]
	v_mfma_f32_16x16x32_bf16 v[138:141], v[146:149], v[162:165], v[138:141]
	v_mfma_f32_16x16x32_bf16 v[130:133], v[154:157], v[162:165], v[130:133]
	v_mfma_f32_16x16x32_bf16 v[118:121], v[146:149], v[170:173], v[118:121]
	v_mfma_f32_16x16x32_bf16 v[114:117], v[154:157], v[170:173], v[114:117]
	v_mfma_f32_16x16x32_bf16 v[98:101], v[146:149], v[196:199], v[98:101]
	v_mfma_f32_16x16x32_bf16 v[94:97], v[154:157], v[196:199], v[94:97]
	v_mfma_f32_16x16x32_bf16 v[78:81], v[146:149], v[204:207], v[78:81]
	v_mfma_f32_16x16x32_bf16 v[74:77], v[154:157], v[204:207], v[74:77]
	v_mfma_f32_16x16x32_bf16 v[138:141], v[150:153], v[166:169], v[138:141]
	v_mfma_f32_16x16x32_bf16 v[130:133], v[158:161], v[166:169], v[130:133]
	v_mfma_f32_16x16x32_bf16 v[118:121], v[150:153], v[174:177], v[118:121]
	v_mfma_f32_16x16x32_bf16 v[114:117], v[158:161], v[174:177], v[114:117]
	v_mfma_f32_16x16x32_bf16 v[98:101], v[150:153], v[200:203], v[98:101]
	v_mfma_f32_16x16x32_bf16 v[94:97], v[158:161], v[200:203], v[94:97]
	v_mfma_f32_16x16x32_bf16 v[78:81], v[150:153], v[208:211], v[78:81]
	v_mfma_f32_16x16x32_bf16 v[74:77], v[158:161], v[208:211], v[74:77]
	s_setprio 0
	s_barrier
	s_add_i32 s37, s37, s53
	s_mov_b32 m0, s37
	ds_read_b128 v[162:165], v221 offset:49152
	ds_read_b128 v[166:169], v221 offset:50176
	ds_read_b128 v[170:173], v221 offset:51200
	ds_read_b128 v[174:177], v221 offset:52224
	s_add_u32 s98, s10, 0x80
	s_addc_u32 s99, s11, 0
	global_load_lds_dwordx4 v184, s[98:99]
	s_add_i32 m0, s37, 0x2000
	s_add_u32 s10, s10, 0x40080
	s_addc_u32 s11, s11, 0
	s_add_i32 s37, s39, s53
	global_load_lds_dwordx4 v188, s[98:99]
	s_mov_b32 m0, s37
	ds_read_b128 v[196:199], v221 offset:53248
	global_load_lds_dwordx4 v184, s[10:11]
	s_add_i32 m0, s37, 0x2000
	ds_read_b128 v[200:203], v221 offset:54272
	global_load_lds_dwordx4 v188, s[10:11]
	s_add_u32 s98, s44, 0xfffc0080
	s_addc_u32 s99, s45, -1
	s_mov_b32 m0, s60
	ds_read_b128 v[204:207], v221 offset:55296
	global_load_lds_dwordx4 v182, s[98:99]
	s_mov_b32 m0, s61
	ds_read_b128 v[208:211], v221 offset:56320
	global_load_lds_dwordx4 v186, s[98:99]
	s_waitcnt vmcnt(8)
	s_waitcnt lgkmcnt(0)
	s_barrier
	s_setprio 1
	v_mfma_f32_16x16x32_bf16 v[62:65], v[66:69], v[162:165], v[62:65]
	v_mfma_f32_16x16x32_bf16 v[54:57], v[86:89], v[162:165], v[54:57]
	v_mfma_f32_16x16x32_bf16 v[46:49], v[66:69], v[170:173], v[46:49]
	v_mfma_f32_16x16x32_bf16 v[42:45], v[86:89], v[170:173], v[42:45]
	v_mfma_f32_16x16x32_bf16 v[30:33], v[66:69], v[196:199], v[30:33]
	v_mfma_f32_16x16x32_bf16 v[26:29], v[86:89], v[196:199], v[26:29]
	v_mfma_f32_16x16x32_bf16 v[14:17], v[66:69], v[204:207], v[14:17]
	v_mfma_f32_16x16x32_bf16 v[10:13], v[86:89], v[204:207], v[10:13]
	v_mfma_f32_16x16x32_bf16 v[62:65], v[70:73], v[166:169], v[62:65]
	v_mfma_f32_16x16x32_bf16 v[54:57], v[106:109], v[166:169], v[54:57]
	v_mfma_f32_16x16x32_bf16 v[46:49], v[70:73], v[174:177], v[46:49]
	v_mfma_f32_16x16x32_bf16 v[42:45], v[106:109], v[174:177], v[42:45]
	v_mfma_f32_16x16x32_bf16 v[30:33], v[70:73], v[200:203], v[30:33]
	v_mfma_f32_16x16x32_bf16 v[26:29], v[106:109], v[200:203], v[26:29]
	v_mfma_f32_16x16x32_bf16 v[14:17], v[70:73], v[208:211], v[14:17]
	v_mfma_f32_16x16x32_bf16 v[10:13], v[106:109], v[208:211], v[10:13]
	v_mfma_f32_16x16x32_bf16 v[58:61], v[146:149], v[162:165], v[58:61]
	v_mfma_f32_16x16x32_bf16 v[50:53], v[154:157], v[162:165], v[50:53]
	v_mfma_f32_16x16x32_bf16 v[38:41], v[146:149], v[170:173], v[38:41]
	v_mfma_f32_16x16x32_bf16 v[34:37], v[154:157], v[170:173], v[34:37]
	v_mfma_f32_16x16x32_bf16 v[22:25], v[146:149], v[196:199], v[22:25]
	v_mfma_f32_16x16x32_bf16 v[18:21], v[154:157], v[196:199], v[18:21]
	v_mfma_f32_16x16x32_bf16 v[6:9], v[146:149], v[204:207], v[6:9]
	v_mfma_f32_16x16x32_bf16 v[2:5], v[154:157], v[204:207], v[2:5]
	v_mfma_f32_16x16x32_bf16 v[58:61], v[150:153], v[166:169], v[58:61]
	v_mfma_f32_16x16x32_bf16 v[50:53], v[158:161], v[166:169], v[50:53]
	v_mfma_f32_16x16x32_bf16 v[38:41], v[150:153], v[174:177], v[38:41]
	v_mfma_f32_16x16x32_bf16 v[34:37], v[158:161], v[174:177], v[34:37]
	v_mfma_f32_16x16x32_bf16 v[22:25], v[150:153], v[200:203], v[22:25]
	v_mfma_f32_16x16x32_bf16 v[18:21], v[158:161], v[200:203], v[18:21]
	v_mfma_f32_16x16x32_bf16 v[6:9], v[150:153], v[208:211], v[6:9]
	v_mfma_f32_16x16x32_bf16 v[2:5], v[158:161], v[208:211], v[2:5]
	s_setprio 0
	s_barrier
	s_add_i32 s22, s22, 2
	s_add_u32 s8, s8, 0x100
	s_addc_u32 s9, s9, 0
	s_add_u32 s5, s5, 0x100
	s_addc_u32 s7, s7, 0
	s_cmp_gt_u32 s22, 13
	s_cbranch_scc1 .Lpeel_x4
.LBB0_991:
	ds_read_b128 v[66:69], v219
	ds_read_b128 v[70:73], v219 offset:1024
	ds_read_b128 v[86:89], v219 offset:2048
	ds_read_b128 v[106:109], v219 offset:3072
	ds_read_b128 v[146:149], v220
	ds_read_b128 v[150:153], v220 offset:1024
	ds_read_b128 v[154:157], v220 offset:2048
	ds_read_b128 v[158:161], v220 offset:3072
	s_add_u32 s10, s8, 0xfffc0080
	s_addc_u32 s11, s9, -1
	s_cmp_eq_u32 s22, 12
	s_cselect_b32 s45, s1, s11
	s_cselect_b32 s44, s2, s10
	s_cselect_b32 s11, s3, s7
	s_cselect_b32 s10, s4, s5
	s_add_i32 m0, s54, 0xc000
	ds_read_b128 v[162:165], v221
	ds_read_b128 v[166:169], v221 offset:1024
	ds_read_b128 v[170:173], v221 offset:2048
	ds_read_b128 v[174:177], v221 offset:3072
	ds_read_b128 v[196:199], v221 offset:4096
	ds_read_b128 v[200:203], v221 offset:5120
	ds_read_b128 v[204:207], v221 offset:6144
	global_load_lds_dwordx4 v192, s[8:9]
	s_add_i32 m0, s54, 0xe000
	ds_read_b128 v[208:211], v221 offset:7168
	global_load_lds_dwordx4 v194, s[8:9]
	s_waitcnt vmcnt(8)
	s_waitcnt lgkmcnt(0)
	s_barrier
	s_setprio 1
	v_mfma_f32_16x16x32_bf16 v[142:145], v[66:69], v[162:165], v[142:145]
	v_mfma_f32_16x16x32_bf16 v[134:137], v[86:89], v[162:165], v[134:137]
	v_mfma_f32_16x16x32_bf16 v[126:129], v[66:69], v[170:173], v[126:129]
	v_mfma_f32_16x16x32_bf16 v[122:125], v[86:89], v[170:173], v[122:125]
	v_mfma_f32_16x16x32_bf16 v[110:113], v[66:69], v[196:199], v[110:113]
	v_mfma_f32_16x16x32_bf16 v[102:105], v[86:89], v[196:199], v[102:105]
	v_mfma_f32_16x16x32_bf16 v[90:93], v[66:69], v[204:207], v[90:93]
	v_mfma_f32_16x16x32_bf16 v[82:85], v[86:89], v[204:207], v[82:85]
	v_mfma_f32_16x16x32_bf16 v[142:145], v[70:73], v[166:169], v[142:145]
	v_mfma_f32_16x16x32_bf16 v[134:137], v[106:109], v[166:169], v[134:137]
	v_mfma_f32_16x16x32_bf16 v[126:129], v[70:73], v[174:177], v[126:129]
	v_mfma_f32_16x16x32_bf16 v[122:125], v[106:109], v[174:177], v[122:125]
	v_mfma_f32_16x16x32_bf16 v[110:113], v[70:73], v[200:203], v[110:113]
	v_mfma_f32_16x16x32_bf16 v[102:105], v[106:109], v[200:203], v[102:105]
	v_mfma_f32_16x16x32_bf16 v[90:93], v[70:73], v[208:211], v[90:93]
	v_mfma_f32_16x16x32_bf16 v[82:85], v[106:109], v[208:211], v[82:85]
	v_mfma_f32_16x16x32_bf16 v[138:141], v[146:149], v[162:165], v[138:141]
	v_mfma_f32_16x16x32_bf16 v[130:133], v[154:157], v[162:165], v[130:133]
	v_mfma_f32_16x16x32_bf16 v[118:121], v[146:149], v[170:173], v[118:121]
	v_mfma_f32_16x16x32_bf16 v[114:117], v[154:157], v[170:173], v[114:117]
	v_mfma_f32_16x16x32_bf16 v[98:101], v[146:149], v[196:199], v[98:101]
	v_mfma_f32_16x16x32_bf16 v[94:97], v[154:157], v[196:199], v[94:97]
	v_mfma_f32_16x16x32_bf16 v[78:81], v[146:149], v[204:207], v[78:81]
	v_mfma_f32_16x16x32_bf16 v[74:77], v[154:157], v[204:207], v[74:77]
	v_mfma_f32_16x16x32_bf16 v[138:141], v[150:153], v[166:169], v[138:141]
	v_mfma_f32_16x16x32_bf16 v[130:133], v[158:161], v[166:169], v[130:133]
	v_mfma_f32_16x16x32_bf16 v[118:121], v[150:153], v[174:177], v[118:121]
	v_mfma_f32_16x16x32_bf16 v[114:117], v[158:161], v[174:177], v[114:117]
	v_mfma_f32_16x16x32_bf16 v[98:101], v[150:153], v[200:203], v[98:101]
	v_mfma_f32_16x16x32_bf16 v[94:97], v[158:161], v[200:203], v[94:97]
	v_mfma_f32_16x16x32_bf16 v[78:81], v[150:153], v[208:211], v[78:81]
	v_mfma_f32_16x16x32_bf16 v[74:77], v[158:161], v[208:211], v[74:77]
	s_setprio 0
	s_barrier
	s_add_i32 s37, s62, s53
	s_mov_b32 m0, s37
	ds_read_b128 v[162:165], v221 offset:16384
	ds_read_b128 v[166:169], v221 offset:17408
	ds_read_b128 v[170:173], v221 offset:18432
	ds_read_b128 v[174:177], v221 offset:19456
	global_load_lds_dwordx4 v184, s[10:11]
	s_add_i32 m0, s37, 0x2000
	s_add_u32 s46, s10, 0x40000
	s_addc_u32 s47, s11, 0
	s_add_i32 s37, s63, s53
	global_load_lds_dwordx4 v188, s[10:11]
	s_mov_b32 m0, s37
	ds_read_b128 v[196:199], v221 offset:20480
	global_load_lds_dwordx4 v184, s[46:47]
	s_add_i32 m0, s37, 0x2000
	ds_read_b128 v[200:203], v221 offset:21504
	global_load_lds_dwordx4 v188, s[46:47]
	s_mov_b32 m0, s54
	ds_read_b128 v[204:207], v221 offset:22528
	global_load_lds_dwordx4 v182, s[44:45]
	s_mov_b32 m0, s55
	ds_read_b128 v[208:211], v221 offset:23552
	global_load_lds_dwordx4 v186, s[44:45]
	s_waitcnt vmcnt(8)
	s_waitcnt lgkmcnt(0)
	s_barrier
	s_setprio 1
	v_mfma_f32_16x16x32_bf16 v[62:65], v[66:69], v[162:165], v[62:65]
	v_mfma_f32_16x16x32_bf16 v[54:57], v[86:89], v[162:165], v[54:57]
	v_mfma_f32_16x16x32_bf16 v[46:49], v[66:69], v[170:173], v[46:49]
	v_mfma_f32_16x16x32_bf16 v[42:45], v[86:89], v[170:173], v[42:45]
	v_mfma_f32_16x16x32_bf16 v[30:33], v[66:69], v[196:199], v[30:33]
	v_mfma_f32_16x16x32_bf16 v[26:29], v[86:89], v[196:199], v[26:29]
	v_mfma_f32_16x16x32_bf16 v[14:17], v[66:69], v[204:207], v[14:17]
	v_mfma_f32_16x16x32_bf16 v[10:13], v[86:89], v[204:207], v[10:13]
	v_mfma_f32_16x16x32_bf16 v[62:65], v[70:73], v[166:169], v[62:65]
	v_mfma_f32_16x16x32_bf16 v[54:57], v[106:109], v[166:169], v[54:57]
	v_mfma_f32_16x16x32_bf16 v[46:49], v[70:73], v[174:177], v[46:49]
	v_mfma_f32_16x16x32_bf16 v[42:45], v[106:109], v[174:177], v[42:45]
	v_mfma_f32_16x16x32_bf16 v[30:33], v[70:73], v[200:203], v[30:33]
	v_mfma_f32_16x16x32_bf16 v[26:29], v[106:109], v[200:203], v[26:29]
	v_mfma_f32_16x16x32_bf16 v[14:17], v[70:73], v[208:211], v[14:17]
	v_mfma_f32_16x16x32_bf16 v[10:13], v[106:109], v[208:211], v[10:13]
	v_mfma_f32_16x16x32_bf16 v[58:61], v[146:149], v[162:165], v[58:61]
	v_mfma_f32_16x16x32_bf16 v[50:53], v[154:157], v[162:165], v[50:53]
	v_mfma_f32_16x16x32_bf16 v[38:41], v[146:149], v[170:173], v[38:41]
	v_mfma_f32_16x16x32_bf16 v[34:37], v[154:157], v[170:173], v[34:37]
	v_mfma_f32_16x16x32_bf16 v[22:25], v[146:149], v[196:199], v[22:25]
	v_mfma_f32_16x16x32_bf16 v[18:21], v[154:157], v[196:199], v[18:21]
	v_mfma_f32_16x16x32_bf16 v[6:9], v[146:149], v[204:207], v[6:9]
	v_mfma_f32_16x16x32_bf16 v[2:5], v[154:157], v[204:207], v[2:5]
	v_mfma_f32_16x16x32_bf16 v[58:61], v[150:153], v[166:169], v[58:61]
	v_mfma_f32_16x16x32_bf16 v[50:53], v[158:161], v[166:169], v[50:53]
	v_mfma_f32_16x16x32_bf16 v[38:41], v[150:153], v[174:177], v[38:41]
	v_mfma_f32_16x16x32_bf16 v[34:37], v[158:161], v[174:177], v[34:37]
	v_mfma_f32_16x16x32_bf16 v[22:25], v[150:153], v[200:203], v[22:25]
	v_mfma_f32_16x16x32_bf16 v[18:21], v[158:161], v[200:203], v[18:21]
	v_mfma_f32_16x16x32_bf16 v[6:9], v[150:153], v[208:211], v[6:9]
	v_mfma_f32_16x16x32_bf16 v[2:5], v[158:161], v[208:211], v[2:5]
	s_setprio 0
	s_barrier
	s_add_i32 s37, 0, 0x18000
	s_add_i32 s39, 0, 0x1c000
	ds_read_b128 v[66:69], v254
	ds_read_b128 v[70:73], v254 offset:1024
	ds_read_b128 v[86:89], v254 offset:2048
	ds_read_b128 v[106:109], v254 offset:3072
	ds_read_b128 v[146:149], v255
	ds_read_b128 v[150:153], v255 offset:1024
	ds_read_b128 v[154:157], v255 offset:2048
	ds_read_b128 v[158:161], v255 offset:3072
	s_add_u32 s44, s44, 0x40000
	s_addc_u32 s45, s45, 0
	s_mov_b32 m0, s56
	ds_read_b128 v[162:165], v221 offset:32768
	ds_read_b128 v[166:169], v221 offset:33792
	ds_read_b128 v[170:173], v221 offset:34816
	ds_read_b128 v[174:177], v221 offset:35840
	ds_read_b128 v[196:199], v221 offset:36864
	ds_read_b128 v[200:203], v221 offset:37888
	ds_read_b128 v[204:207], v221 offset:38912
	global_load_lds_dwordx4 v182, s[44:45]
	s_mov_b32 m0, s57
	ds_read_b128 v[208:211], v221 offset:39936
	global_load_lds_dwordx4 v186, s[44:45]
	s_waitcnt vmcnt(8)
	s_waitcnt lgkmcnt(0)
	s_barrier
	s_setprio 1
	v_mfma_f32_16x16x32_bf16 v[142:145], v[66:69], v[162:165], v[142:145]
	v_mfma_f32_16x16x32_bf16 v[134:137], v[86:89], v[162:165], v[134:137]
	v_mfma_f32_16x16x32_bf16 v[126:129], v[66:69], v[170:173], v[126:129]
	v_mfma_f32_16x16x32_bf16 v[122:125], v[86:89], v[170:173], v[122:125]
	v_mfma_f32_16x16x32_bf16 v[110:113], v[66:69], v[196:199], v[110:113]
	v_mfma_f32_16x16x32_bf16 v[102:105], v[86:89], v[196:199], v[102:105]
	v_mfma_f32_16x16x32_bf16 v[90:93], v[66:69], v[204:207], v[90:93]
	v_mfma_f32_16x16x32_bf16 v[82:85], v[86:89], v[204:207], v[82:85]
	v_mfma_f32_16x16x32_bf16 v[142:145], v[70:73], v[166:169], v[142:145]
	v_mfma_f32_16x16x32_bf16 v[134:137], v[106:109], v[166:169], v[134:137]
	v_mfma_f32_16x16x32_bf16 v[126:129], v[70:73], v[174:177], v[126:129]
	v_mfma_f32_16x16x32_bf16 v[122:125], v[106:109], v[174:177], v[122:125]
	v_mfma_f32_16x16x32_bf16 v[110:113], v[70:73], v[200:203], v[110:113]
	v_mfma_f32_16x16x32_bf16 v[102:105], v[106:109], v[200:203], v[102:105]
	v_mfma_f32_16x16x32_bf16 v[90:93], v[70:73], v[208:211], v[90:93]
	v_mfma_f32_16x16x32_bf16 v[82:85], v[106:109], v[208:211], v[82:85]
	v_mfma_f32_16x16x32_bf16 v[138:141], v[146:149], v[162:165], v[138:141]
	v_mfma_f32_16x16x32_bf16 v[130:133], v[154:157], v[162:165], v[130:133]
	v_mfma_f32_16x16x32_bf16 v[118:121], v[146:149], v[170:173], v[118:121]
	v_mfma_f32_16x16x32_bf16 v[114:117], v[154:157], v[170:173], v[114:117]
	v_mfma_f32_16x16x32_bf16 v[98:101], v[146:149], v[196:199], v[98:101]
	v_mfma_f32_16x16x32_bf16 v[94:97], v[154:157], v[196:199], v[94:97]
	v_mfma_f32_16x16x32_bf16 v[78:81], v[146:149], v[204:207], v[78:81]
	v_mfma_f32_16x16x32_bf16 v[74:77], v[154:157], v[204:207], v[74:77]
	v_mfma_f32_16x16x32_bf16 v[138:141], v[150:153], v[166:169], v[138:141]
	v_mfma_f32_16x16x32_bf16 v[130:133], v[158:161], v[166:169], v[130:133]
	v_mfma_f32_16x16x32_bf16 v[118:121], v[150:153], v[174:177], v[118:121]
	v_mfma_f32_16x16x32_bf16 v[114:117], v[158:161], v[174:177], v[114:117]
	v_mfma_f32_16x16x32_bf16 v[98:101], v[150:153], v[200:203], v[98:101]
	v_mfma_f32_16x16x32_bf16 v[94:97], v[158:161], v[200:203], v[94:97]
	v_mfma_f32_16x16x32_bf16 v[78:81], v[150:153], v[208:211], v[78:81]
	v_mfma_f32_16x16x32_bf16 v[74:77], v[158:161], v[208:211], v[74:77]
	s_setprio 0
	s_barrier
	s_add_i32 s37, s37, s53
	s_mov_b32 m0, s37
	ds_read_b128 v[162:165], v221 offset:49152
	ds_read_b128 v[166:169], v221 offset:50176
	ds_read_b128 v[170:173], v221 offset:51200
	ds_read_b128 v[174:177], v221 offset:52224
	s_add_u32 s98, s10, 0x80
	s_addc_u32 s99, s11, 0
	global_load_lds_dwordx4 v184, s[98:99]
	s_add_i32 m0, s37, 0x2000
	s_add_u32 s10, s10, 0x40080
	s_addc_u32 s11, s11, 0
	s_add_i32 s37, s39, s53
	global_load_lds_dwordx4 v188, s[98:99]
	s_mov_b32 m0, s37
	ds_read_b128 v[196:199], v221 offset:53248
	global_load_lds_dwordx4 v184, s[10:11]
	s_add_i32 m0, s37, 0x2000
	ds_read_b128 v[200:203], v221 offset:54272
	global_load_lds_dwordx4 v188, s[10:11]
	s_add_u32 s98, s44, 0xfffc0080
	s_addc_u32 s99, s45, -1
	s_mov_b32 m0, s60
	ds_read_b128 v[204:207], v221 offset:55296
	global_load_lds_dwordx4 v182, s[98:99]
	s_mov_b32 m0, s61
	ds_read_b128 v[208:211], v221 offset:56320
	global_load_lds_dwordx4 v186, s[98:99]
	s_waitcnt vmcnt(8)
	s_waitcnt lgkmcnt(0)
	s_barrier
	s_setprio 1
	v_mfma_f32_16x16x32_bf16 v[62:65], v[66:69], v[162:165], v[62:65]
	v_mfma_f32_16x16x32_bf16 v[54:57], v[86:89], v[162:165], v[54:57]
	v_mfma_f32_16x16x32_bf16 v[46:49], v[66:69], v[170:173], v[46:49]
	v_mfma_f32_16x16x32_bf16 v[42:45], v[86:89], v[170:173], v[42:45]
	v_mfma_f32_16x16x32_bf16 v[30:33], v[66:69], v[196:199], v[30:33]
	v_mfma_f32_16x16x32_bf16 v[26:29], v[86:89], v[196:199], v[26:29]
	v_mfma_f32_16x16x32_bf16 v[14:17], v[66:69], v[204:207], v[14:17]
	v_mfma_f32_16x16x32_bf16 v[10:13], v[86:89], v[204:207], v[10:13]
	v_mfma_f32_16x16x32_bf16 v[62:65], v[70:73], v[166:169], v[62:65]
	v_mfma_f32_16x16x32_bf16 v[54:57], v[106:109], v[166:169], v[54:57]
	v_mfma_f32_16x16x32_bf16 v[46:49], v[70:73], v[174:177], v[46:49]
	v_mfma_f32_16x16x32_bf16 v[42:45], v[106:109], v[174:177], v[42:45]
	v_mfma_f32_16x16x32_bf16 v[30:33], v[70:73], v[200:203], v[30:33]
	v_mfma_f32_16x16x32_bf16 v[26:29], v[106:109], v[200:203], v[26:29]
	v_mfma_f32_16x16x32_bf16 v[14:17], v[70:73], v[208:211], v[14:17]
	v_mfma_f32_16x16x32_bf16 v[10:13], v[106:109], v[208:211], v[10:13]
	v_mfma_f32_16x16x32_bf16 v[58:61], v[146:149], v[162:165], v[58:61]
	v_mfma_f32_16x16x32_bf16 v[50:53], v[154:157], v[162:165], v[50:53]
	v_mfma_f32_16x16x32_bf16 v[38:41], v[146:149], v[170:173], v[38:41]
	v_mfma_f32_16x16x32_bf16 v[34:37], v[154:157], v[170:173], v[34:37]
	v_mfma_f32_16x16x32_bf16 v[22:25], v[146:149], v[196:199], v[22:25]
	v_mfma_f32_16x16x32_bf16 v[18:21], v[154:157], v[196:199], v[18:21]
	v_mfma_f32_16x16x32_bf16 v[6:9], v[146:149], v[204:207], v[6:9]
	v_mfma_f32_16x16x32_bf16 v[2:5], v[154:157], v[204:207], v[2:5]
	v_mfma_f32_16x16x32_bf16 v[58:61], v[150:153], v[166:169], v[58:61]
	v_mfma_f32_16x16x32_bf16 v[50:53], v[158:161], v[166:169], v[50:53]
	v_mfma_f32_16x16x32_bf16 v[38:41], v[150:153], v[174:177], v[38:41]
	v_mfma_f32_16x16x32_bf16 v[34:37], v[158:161], v[174:177], v[34:37]
	v_mfma_f32_16x16x32_bf16 v[22:25], v[150:153], v[200:203], v[22:25]
	v_mfma_f32_16x16x32_bf16 v[18:21], v[158:161], v[200:203], v[18:21]
	v_mfma_f32_16x16x32_bf16 v[6:9], v[150:153], v[208:211], v[6:9]
	v_mfma_f32_16x16x32_bf16 v[2:5], v[158:161], v[208:211], v[2:5]
	s_setprio 0
	s_barrier
	s_add_i32 s22, s22, 2
	s_add_u32 s8, s8, 0x100
	s_addc_u32 s9, s9, 0
	s_add_u32 s5, s5, 0x100
	s_addc_u32 s7, s7, 0
	s_cmp_gt_u32 s22, 13
	s_cbranch_scc0 .LBB0_991

.LBB0_1107:
	s_and_b64 s[20:21], s[26:27], exec
	s_cselect_b32 s21, s35, s23
	s_cselect_b32 s20, s34, s22
	s_add_u32 s22, s22, 0xb0080
	s_addc_u32 s23, s23, 0
	s_add_u32 s49, s24, 0x100
	s_addc_u32 s50, s25, 0
	s_mov_b32 s51, -2
	ds_read_b128 v[142:145], v150
	ds_read_b128 v[156:159], v150 offset:1024
	ds_read_b128 v[160:163], v150 offset:2048
	ds_read_b128 v[164:167], v150 offset:3072
	ds_read_b128 v[168:171], v151
	ds_read_b128 v[172:175], v151 offset:1024
	ds_read_b128 v[180:183], v151 offset:2048
	ds_read_b128 v[184:187], v151 offset:3072
	s_add_u32 s24, s22, 0xfff50080
	s_addc_u32 s25, s23, -1
	s_cmp_eq_u32 s51, 40
	s_cselect_b32 s27, s21, s25
	s_cselect_b32 s26, s20, s24
	s_cselect_b32 s25, s19, s50
	s_cselect_b32 s24, s18, s49
	s_mov_b32 m0, s36
	ds_read_b128 v[188:191], v152
	ds_read_b128 v[192:195], v152 offset:1024
	ds_read_b128 v[196:199], v152 offset:2048
	ds_read_b128 v[200:203], v152 offset:3072
	ds_read_b128 v[204:207], v152 offset:4096
	ds_read_b128 v[208:211], v152 offset:5120
	ds_read_b128 v[212:215], v152 offset:6144
	global_load_lds_dwordx4 v138, s[22:23]
	s_mov_b32 m0, s37
	ds_read_b128 v[216:219], v152 offset:7168
	global_load_lds_dwordx4 v140, s[22:23]
	s_waitcnt vmcnt(8)
	s_waitcnt lgkmcnt(0)
	s_barrier
	s_setprio 1
	v_mfma_f32_16x16x32_bf16 v[126:129], v[142:145], v[188:191], 0
	v_mfma_f32_16x16x32_bf16 v[122:125], v[160:163], v[188:191], 0
	v_mfma_f32_16x16x32_bf16 v[110:113], v[142:145], v[196:199], 0
	v_mfma_f32_16x16x32_bf16 v[106:109], v[160:163], v[196:199], 0
	v_mfma_f32_16x16x32_bf16 v[94:97], v[142:145], v[204:207], 0
	v_mfma_f32_16x16x32_bf16 v[90:93], v[160:163], v[204:207], 0
	v_mfma_f32_16x16x32_bf16 v[78:81], v[142:145], v[212:215], 0
	v_mfma_f32_16x16x32_bf16 v[74:77], v[160:163], v[212:215], 0
	v_mfma_f32_16x16x32_bf16 v[126:129], v[156:159], v[192:195], v[126:129]
	v_mfma_f32_16x16x32_bf16 v[122:125], v[164:167], v[192:195], v[122:125]
	v_mfma_f32_16x16x32_bf16 v[110:113], v[156:159], v[200:203], v[110:113]
	v_mfma_f32_16x16x32_bf16 v[106:109], v[164:167], v[200:203], v[106:109]
	v_mfma_f32_16x16x32_bf16 v[94:97], v[156:159], v[208:211], v[94:97]
	v_mfma_f32_16x16x32_bf16 v[90:93], v[164:167], v[208:211], v[90:93]
	v_mfma_f32_16x16x32_bf16 v[78:81], v[156:159], v[216:219], v[78:81]
	v_mfma_f32_16x16x32_bf16 v[74:77], v[164:167], v[216:219], v[74:77]
	v_mfma_f32_16x16x32_bf16 v[118:121], v[168:171], v[188:191], 0
	v_mfma_f32_16x16x32_bf16 v[114:117], v[180:183], v[188:191], 0
	v_mfma_f32_16x16x32_bf16 v[102:105], v[168:171], v[196:199], 0
	v_mfma_f32_16x16x32_bf16 v[98:101], v[180:183], v[196:199], 0
	v_mfma_f32_16x16x32_bf16 v[86:89], v[168:171], v[204:207], 0
	v_mfma_f32_16x16x32_bf16 v[82:85], v[180:183], v[204:207], 0
	v_mfma_f32_16x16x32_bf16 v[70:73], v[168:171], v[212:215], 0
	v_mfma_f32_16x16x32_bf16 v[66:69], v[180:183], v[212:215], 0
	v_mfma_f32_16x16x32_bf16 v[118:121], v[172:175], v[192:195], v[118:121]
	v_mfma_f32_16x16x32_bf16 v[114:117], v[184:187], v[192:195], v[114:117]
	v_mfma_f32_16x16x32_bf16 v[102:105], v[172:175], v[200:203], v[102:105]
	v_mfma_f32_16x16x32_bf16 v[98:101], v[184:187], v[200:203], v[98:101]
	v_mfma_f32_16x16x32_bf16 v[86:89], v[172:175], v[208:211], v[86:89]
	v_mfma_f32_16x16x32_bf16 v[82:85], v[184:187], v[208:211], v[82:85]
	v_mfma_f32_16x16x32_bf16 v[70:73], v[172:175], v[216:219], v[70:73]
	v_mfma_f32_16x16x32_bf16 v[66:69], v[184:187], v[216:219], v[66:69]
	s_setprio 0
	s_barrier
	s_mov_b32 m0, s38
	s_add_u32 s52, s24, 0xb0000
	ds_read_b128 v[188:191], v152 offset:16384
	ds_read_b128 v[192:195], v152 offset:17408
	ds_read_b128 v[196:199], v152 offset:18432
	ds_read_b128 v[200:203], v152 offset:19456
	global_load_lds_dwordx4 v134, s[24:25]
	s_mov_b32 m0, s39
	s_addc_u32 s53, s25, 0
	global_load_lds_dwordx4 v130, s[24:25]
	s_mov_b32 m0, s40
	ds_read_b128 v[204:207], v152 offset:20480
	global_load_lds_dwordx4 v134, s[52:53]
	s_mov_b32 m0, s41
	ds_read_b128 v[208:211], v152 offset:21504
	global_load_lds_dwordx4 v130, s[52:53]
	s_mov_b32 m0, s4
	ds_read_b128 v[212:215], v152 offset:22528
	global_load_lds_dwordx4 v136, s[26:27]
	s_mov_b32 m0, s5
	ds_read_b128 v[216:219], v152 offset:23552
	global_load_lds_dwordx4 v132, s[26:27]
	s_waitcnt vmcnt(8)
	s_waitcnt lgkmcnt(0)
	s_barrier
	s_setprio 1
	v_mfma_f32_16x16x32_bf16 v[62:65], v[142:145], v[188:191], 0
	v_mfma_f32_16x16x32_bf16 v[58:61], v[160:163], v[188:191], 0
	v_mfma_f32_16x16x32_bf16 v[46:49], v[142:145], v[196:199], 0
	v_mfma_f32_16x16x32_bf16 v[42:45], v[160:163], v[196:199], 0
	v_mfma_f32_16x16x32_bf16 v[34:37], v[142:145], v[204:207], 0
	v_mfma_f32_16x16x32_bf16 v[26:29], v[160:163], v[204:207], 0
	v_mfma_f32_16x16x32_bf16 v[18:21], v[142:145], v[212:215], 0
	v_mfma_f32_16x16x32_bf16 v[10:13], v[160:163], v[212:215], 0
	v_mfma_f32_16x16x32_bf16 v[62:65], v[156:159], v[192:195], v[62:65]
	v_mfma_f32_16x16x32_bf16 v[58:61], v[164:167], v[192:195], v[58:61]
	v_mfma_f32_16x16x32_bf16 v[46:49], v[156:159], v[200:203], v[46:49]
	v_mfma_f32_16x16x32_bf16 v[42:45], v[164:167], v[200:203], v[42:45]
	v_mfma_f32_16x16x32_bf16 v[34:37], v[156:159], v[208:211], v[34:37]
	v_mfma_f32_16x16x32_bf16 v[26:29], v[164:167], v[208:211], v[26:29]
	v_mfma_f32_16x16x32_bf16 v[18:21], v[156:159], v[216:219], v[18:21]
	v_mfma_f32_16x16x32_bf16 v[10:13], v[164:167], v[216:219], v[10:13]
	v_mfma_f32_16x16x32_bf16 v[54:57], v[168:171], v[188:191], 0
	v_mfma_f32_16x16x32_bf16 v[50:53], v[180:183], v[188:191], 0
	v_mfma_f32_16x16x32_bf16 v[38:41], v[168:171], v[196:199], 0
	v_mfma_f32_16x16x32_bf16 v[30:33], v[180:183], v[196:199], 0
	v_mfma_f32_16x16x32_bf16 v[22:25], v[168:171], v[204:207], 0
	v_mfma_f32_16x16x32_bf16 v[14:17], v[180:183], v[204:207], 0
	v_mfma_f32_16x16x32_bf16 v[6:9], v[168:171], v[212:215], 0
	v_mfma_f32_16x16x32_bf16 v[2:5], v[180:183], v[212:215], 0
	v_mfma_f32_16x16x32_bf16 v[54:57], v[172:175], v[192:195], v[54:57]
	v_mfma_f32_16x16x32_bf16 v[50:53], v[184:187], v[192:195], v[50:53]
	v_mfma_f32_16x16x32_bf16 v[38:41], v[172:175], v[200:203], v[38:41]
	v_mfma_f32_16x16x32_bf16 v[30:33], v[184:187], v[200:203], v[30:33]
	v_mfma_f32_16x16x32_bf16 v[22:25], v[172:175], v[208:211], v[22:25]
	v_mfma_f32_16x16x32_bf16 v[14:17], v[184:187], v[208:211], v[14:17]
	v_mfma_f32_16x16x32_bf16 v[6:9], v[172:175], v[216:219], v[6:9]
	v_mfma_f32_16x16x32_bf16 v[2:5], v[184:187], v[216:219], v[2:5]
	s_setprio 0
	s_barrier
	ds_read_b128 v[142:145], v153
	ds_read_b128 v[156:159], v153 offset:1024
	ds_read_b128 v[160:163], v153 offset:2048
	ds_read_b128 v[164:167], v153 offset:3072
	ds_read_b128 v[168:171], v154
	ds_read_b128 v[172:175], v154 offset:1024
	ds_read_b128 v[180:183], v154 offset:2048
	ds_read_b128 v[184:187], v154 offset:3072
	s_add_u32 s26, s26, 0xb0000
	s_addc_u32 s27, s27, 0
	s_mov_b32 m0, s29
	ds_read_b128 v[188:191], v152 offset:32768
	ds_read_b128 v[192:195], v152 offset:33792
	ds_read_b128 v[196:199], v152 offset:34816
	ds_read_b128 v[200:203], v152 offset:35840
	ds_read_b128 v[204:207], v152 offset:36864
	ds_read_b128 v[208:211], v152 offset:37888
	ds_read_b128 v[212:215], v152 offset:38912
	global_load_lds_dwordx4 v136, s[26:27]
	s_mov_b32 m0, s30
	ds_read_b128 v[216:219], v152 offset:39936
	global_load_lds_dwordx4 v132, s[26:27]
	s_waitcnt vmcnt(8)
	s_waitcnt lgkmcnt(0)
	s_barrier
	s_setprio 1
	v_mfma_f32_16x16x32_bf16 v[126:129], v[142:145], v[188:191], v[126:129]
	v_mfma_f32_16x16x32_bf16 v[122:125], v[160:163], v[188:191], v[122:125]
	v_mfma_f32_16x16x32_bf16 v[110:113], v[142:145], v[196:199], v[110:113]
	v_mfma_f32_16x16x32_bf16 v[106:109], v[160:163], v[196:199], v[106:109]
	v_mfma_f32_16x16x32_bf16 v[94:97], v[142:145], v[204:207], v[94:97]
	v_mfma_f32_16x16x32_bf16 v[90:93], v[160:163], v[204:207], v[90:93]
	v_mfma_f32_16x16x32_bf16 v[78:81], v[142:145], v[212:215], v[78:81]
	v_mfma_f32_16x16x32_bf16 v[74:77], v[160:163], v[212:215], v[74:77]
	v_mfma_f32_16x16x32_bf16 v[126:129], v[156:159], v[192:195], v[126:129]
	v_mfma_f32_16x16x32_bf16 v[122:125], v[164:167], v[192:195], v[122:125]
	v_mfma_f32_16x16x32_bf16 v[110:113], v[156:159], v[200:203], v[110:113]
	v_mfma_f32_16x16x32_bf16 v[106:109], v[164:167], v[200:203], v[106:109]
	v_mfma_f32_16x16x32_bf16 v[94:97], v[156:159], v[208:211], v[94:97]
	v_mfma_f32_16x16x32_bf16 v[90:93], v[164:167], v[208:211], v[90:93]
	v_mfma_f32_16x16x32_bf16 v[78:81], v[156:159], v[216:219], v[78:81]
	v_mfma_f32_16x16x32_bf16 v[74:77], v[164:167], v[216:219], v[74:77]
	v_mfma_f32_16x16x32_bf16 v[118:121], v[168:171], v[188:191], v[118:121]
	v_mfma_f32_16x16x32_bf16 v[114:117], v[180:183], v[188:191], v[114:117]
	v_mfma_f32_16x16x32_bf16 v[102:105], v[168:171], v[196:199], v[102:105]
	v_mfma_f32_16x16x32_bf16 v[98:101], v[180:183], v[196:199], v[98:101]
	v_mfma_f32_16x16x32_bf16 v[86:89], v[168:171], v[204:207], v[86:89]
	v_mfma_f32_16x16x32_bf16 v[82:85], v[180:183], v[204:207], v[82:85]
	v_mfma_f32_16x16x32_bf16 v[70:73], v[168:171], v[212:215], v[70:73]
	v_mfma_f32_16x16x32_bf16 v[66:69], v[180:183], v[212:215], v[66:69]
	v_mfma_f32_16x16x32_bf16 v[118:121], v[172:175], v[192:195], v[118:121]
	v_mfma_f32_16x16x32_bf16 v[114:117], v[184:187], v[192:195], v[114:117]
	v_mfma_f32_16x16x32_bf16 v[102:105], v[172:175], v[200:203], v[102:105]
	v_mfma_f32_16x16x32_bf16 v[98:101], v[184:187], v[200:203], v[98:101]
	v_mfma_f32_16x16x32_bf16 v[86:89], v[172:175], v[208:211], v[86:89]
	v_mfma_f32_16x16x32_bf16 v[82:85], v[184:187], v[208:211], v[82:85]
	v_mfma_f32_16x16x32_bf16 v[70:73], v[172:175], v[216:219], v[70:73]
	v_mfma_f32_16x16x32_bf16 v[66:69], v[184:187], v[216:219], v[66:69]
	s_setprio 0
	s_barrier
	s_mov_b32 m0, s42
	ds_read_b128 v[188:191], v152 offset:49152
	ds_read_b128 v[192:195], v152 offset:50176
	ds_read_b128 v[196:199], v152 offset:51200
	ds_read_b128 v[200:203], v152 offset:52224
	s_add_u32 s98, s24, 0x80
	s_addc_u32 s99, s25, 0
	global_load_lds_dwordx4 v134, s[98:99]
	s_mov_b32 m0, s43
	s_add_u32 s24, s24, 0xb0080
	s_addc_u32 s25, s25, 0
	global_load_lds_dwordx4 v130, s[98:99]
	s_mov_b32 m0, s44
	ds_read_b128 v[204:207], v152 offset:53248
	global_load_lds_dwordx4 v134, s[24:25]
	s_mov_b32 m0, s45
	ds_read_b128 v[208:211], v152 offset:54272
	global_load_lds_dwordx4 v130, s[24:25]
	s_add_u32 s98, s26, 0xfff50080
	s_addc_u32 s99, s27, -1
	s_mov_b32 m0, s0
	ds_read_b128 v[212:215], v152 offset:55296
	global_load_lds_dwordx4 v136, s[98:99]
	s_mov_b32 m0, s1
	ds_read_b128 v[216:219], v152 offset:56320
	global_load_lds_dwordx4 v132, s[98:99]
	s_waitcnt vmcnt(8)
	s_waitcnt lgkmcnt(0)
	s_barrier
	s_setprio 1
	v_mfma_f32_16x16x32_bf16 v[62:65], v[142:145], v[188:191], v[62:65]
	v_mfma_f32_16x16x32_bf16 v[58:61], v[160:163], v[188:191], v[58:61]
	v_mfma_f32_16x16x32_bf16 v[46:49], v[142:145], v[196:199], v[46:49]
	v_mfma_f32_16x16x32_bf16 v[42:45], v[160:163], v[196:199], v[42:45]
	v_mfma_f32_16x16x32_bf16 v[34:37], v[142:145], v[204:207], v[34:37]
	v_mfma_f32_16x16x32_bf16 v[26:29], v[160:163], v[204:207], v[26:29]
	v_mfma_f32_16x16x32_bf16 v[18:21], v[142:145], v[212:215], v[18:21]
	v_mfma_f32_16x16x32_bf16 v[10:13], v[160:163], v[212:215], v[10:13]
	v_mfma_f32_16x16x32_bf16 v[62:65], v[156:159], v[192:195], v[62:65]
	v_mfma_f32_16x16x32_bf16 v[58:61], v[164:167], v[192:195], v[58:61]
	v_mfma_f32_16x16x32_bf16 v[46:49], v[156:159], v[200:203], v[46:49]
	v_mfma_f32_16x16x32_bf16 v[42:45], v[164:167], v[200:203], v[42:45]
	v_mfma_f32_16x16x32_bf16 v[34:37], v[156:159], v[208:211], v[34:37]
	v_mfma_f32_16x16x32_bf16 v[26:29], v[164:167], v[208:211], v[26:29]
	v_mfma_f32_16x16x32_bf16 v[18:21], v[156:159], v[216:219], v[18:21]
	v_mfma_f32_16x16x32_bf16 v[10:13], v[164:167], v[216:219], v[10:13]
	v_mfma_f32_16x16x32_bf16 v[54:57], v[168:171], v[188:191], v[54:57]
	v_mfma_f32_16x16x32_bf16 v[50:53], v[180:183], v[188:191], v[50:53]
	v_mfma_f32_16x16x32_bf16 v[38:41], v[168:171], v[196:199], v[38:41]
	v_mfma_f32_16x16x32_bf16 v[30:33], v[180:183], v[196:199], v[30:33]
	v_mfma_f32_16x16x32_bf16 v[22:25], v[168:171], v[204:207], v[22:25]
	v_mfma_f32_16x16x32_bf16 v[14:17], v[180:183], v[204:207], v[14:17]
	v_mfma_f32_16x16x32_bf16 v[6:9], v[168:171], v[212:215], v[6:9]
	v_mfma_f32_16x16x32_bf16 v[2:5], v[180:183], v[212:215], v[2:5]
	v_mfma_f32_16x16x32_bf16 v[54:57], v[172:175], v[192:195], v[54:57]
	v_mfma_f32_16x16x32_bf16 v[50:53], v[184:187], v[192:195], v[50:53]
	v_mfma_f32_16x16x32_bf16 v[38:41], v[172:175], v[200:203], v[38:41]
	v_mfma_f32_16x16x32_bf16 v[30:33], v[184:187], v[200:203], v[30:33]
	v_mfma_f32_16x16x32_bf16 v[22:25], v[172:175], v[208:211], v[22:25]
	v_mfma_f32_16x16x32_bf16 v[14:17], v[184:187], v[208:211], v[14:17]
	v_mfma_f32_16x16x32_bf16 v[6:9], v[172:175], v[216:219], v[6:9]
	v_mfma_f32_16x16x32_bf16 v[2:5], v[184:187], v[216:219], v[2:5]
	s_setprio 0
	s_barrier
	s_add_i32 s51, s51, 2
	s_add_u32 s22, s22, 0x100
	s_addc_u32 s23, s23, 0
	s_add_u32 s49, s49, 0x100
	s_addc_u32 s50, s50, 0
	s_cmp_gt_u32 s51, 41
	s_cbranch_scc1 .Lpeel_x5
.LBB0_1108:
	ds_read_b128 v[142:145], v150
	ds_read_b128 v[156:159], v150 offset:1024
	ds_read_b128 v[160:163], v150 offset:2048
	ds_read_b128 v[164:167], v150 offset:3072
	ds_read_b128 v[168:171], v151
	ds_read_b128 v[172:175], v151 offset:1024
	ds_read_b128 v[180:183], v151 offset:2048
	ds_read_b128 v[184:187], v151 offset:3072
	s_add_u32 s24, s22, 0xfff50080
	s_addc_u32 s25, s23, -1
	s_cmp_eq_u32 s51, 40
	s_cselect_b32 s27, s21, s25
	s_cselect_b32 s26, s20, s24
	s_cselect_b32 s25, s19, s50
	s_cselect_b32 s24, s18, s49
	s_mov_b32 m0, s36
	ds_read_b128 v[188:191], v152
	ds_read_b128 v[192:195], v152 offset:1024
	ds_read_b128 v[196:199], v152 offset:2048
	ds_read_b128 v[200:203], v152 offset:3072
	ds_read_b128 v[204:207], v152 offset:4096
	ds_read_b128 v[208:211], v152 offset:5120
	ds_read_b128 v[212:215], v152 offset:6144
	global_load_lds_dwordx4 v138, s[22:23]
	s_mov_b32 m0, s37
	ds_read_b128 v[216:219], v152 offset:7168
	global_load_lds_dwordx4 v140, s[22:23]
	s_waitcnt vmcnt(8)
	s_waitcnt lgkmcnt(0)
	s_barrier
	s_setprio 1
	v_mfma_f32_16x16x32_bf16 v[126:129], v[142:145], v[188:191], v[126:129]
	v_mfma_f32_16x16x32_bf16 v[122:125], v[160:163], v[188:191], v[122:125]
	v_mfma_f32_16x16x32_bf16 v[110:113], v[142:145], v[196:199], v[110:113]
	v_mfma_f32_16x16x32_bf16 v[106:109], v[160:163], v[196:199], v[106:109]
	v_mfma_f32_16x16x32_bf16 v[94:97], v[142:145], v[204:207], v[94:97]
	v_mfma_f32_16x16x32_bf16 v[90:93], v[160:163], v[204:207], v[90:93]
	v_mfma_f32_16x16x32_bf16 v[78:81], v[142:145], v[212:215], v[78:81]
	v_mfma_f32_16x16x32_bf16 v[74:77], v[160:163], v[212:215], v[74:77]
	v_mfma_f32_16x16x32_bf16 v[126:129], v[156:159], v[192:195], v[126:129]
	v_mfma_f32_16x16x32_bf16 v[122:125], v[164:167], v[192:195], v[122:125]
	v_mfma_f32_16x16x32_bf16 v[110:113], v[156:159], v[200:203], v[110:113]
	v_mfma_f32_16x16x32_bf16 v[106:109], v[164:167], v[200:203], v[106:109]
	v_mfma_f32_16x16x32_bf16 v[94:97], v[156:159], v[208:211], v[94:97]
	v_mfma_f32_16x16x32_bf16 v[90:93], v[164:167], v[208:211], v[90:93]
	v_mfma_f32_16x16x32_bf16 v[78:81], v[156:159], v[216:219], v[78:81]
	v_mfma_f32_16x16x32_bf16 v[74:77], v[164:167], v[216:219], v[74:77]
	v_mfma_f32_16x16x32_bf16 v[118:121], v[168:171], v[188:191], v[118:121]
	v_mfma_f32_16x16x32_bf16 v[114:117], v[180:183], v[188:191], v[114:117]
	v_mfma_f32_16x16x32_bf16 v[102:105], v[168:171], v[196:199], v[102:105]
	v_mfma_f32_16x16x32_bf16 v[98:101], v[180:183], v[196:199], v[98:101]
	v_mfma_f32_16x16x32_bf16 v[86:89], v[168:171], v[204:207], v[86:89]
	v_mfma_f32_16x16x32_bf16 v[82:85], v[180:183], v[204:207], v[82:85]
	v_mfma_f32_16x16x32_bf16 v[70:73], v[168:171], v[212:215], v[70:73]
	v_mfma_f32_16x16x32_bf16 v[66:69], v[180:183], v[212:215], v[66:69]
	v_mfma_f32_16x16x32_bf16 v[118:121], v[172:175], v[192:195], v[118:121]
	v_mfma_f32_16x16x32_bf16 v[114:117], v[184:187], v[192:195], v[114:117]
	v_mfma_f32_16x16x32_bf16 v[102:105], v[172:175], v[200:203], v[102:105]
	v_mfma_f32_16x16x32_bf16 v[98:101], v[184:187], v[200:203], v[98:101]
	v_mfma_f32_16x16x32_bf16 v[86:89], v[172:175], v[208:211], v[86:89]
	v_mfma_f32_16x16x32_bf16 v[82:85], v[184:187], v[208:211], v[82:85]
	v_mfma_f32_16x16x32_bf16 v[70:73], v[172:175], v[216:219], v[70:73]
	v_mfma_f32_16x16x32_bf16 v[66:69], v[184:187], v[216:219], v[66:69]
	s_setprio 0
	s_barrier
	s_mov_b32 m0, s38
	s_add_u32 s52, s24, 0xb0000
	ds_read_b128 v[188:191], v152 offset:16384
	ds_read_b128 v[192:195], v152 offset:17408
	ds_read_b128 v[196:199], v152 offset:18432
	ds_read_b128 v[200:203], v152 offset:19456
	global_load_lds_dwordx4 v134, s[24:25]
	s_mov_b32 m0, s39
	s_addc_u32 s53, s25, 0
	global_load_lds_dwordx4 v130, s[24:25]
	s_mov_b32 m0, s40
	ds_read_b128 v[204:207], v152 offset:20480
	global_load_lds_dwordx4 v134, s[52:53]
	s_mov_b32 m0, s41
	ds_read_b128 v[208:211], v152 offset:21504
	global_load_lds_dwordx4 v130, s[52:53]
	s_mov_b32 m0, s4
	ds_read_b128 v[212:215], v152 offset:22528
	global_load_lds_dwordx4 v136, s[26:27]
	s_mov_b32 m0, s5
	ds_read_b128 v[216:219], v152 offset:23552
	global_load_lds_dwordx4 v132, s[26:27]
	s_waitcnt vmcnt(8)
	s_waitcnt lgkmcnt(0)
	s_barrier
	s_setprio 1
	v_mfma_f32_16x16x32_bf16 v[62:65], v[142:145], v[188:191], v[62:65]
	v_mfma_f32_16x16x32_bf16 v[58:61], v[160:163], v[188:191], v[58:61]
	v_mfma_f32_16x16x32_bf16 v[46:49], v[142:145], v[196:199], v[46:49]
	v_mfma_f32_16x16x32_bf16 v[42:45], v[160:163], v[196:199], v[42:45]
	v_mfma_f32_16x16x32_bf16 v[34:37], v[142:145], v[204:207], v[34:37]
	v_mfma_f32_16x16x32_bf16 v[26:29], v[160:163], v[204:207], v[26:29]
	v_mfma_f32_16x16x32_bf16 v[18:21], v[142:145], v[212:215], v[18:21]
	v_mfma_f32_16x16x32_bf16 v[10:13], v[160:163], v[212:215], v[10:13]
	v_mfma_f32_16x16x32_bf16 v[62:65], v[156:159], v[192:195], v[62:65]
	v_mfma_f32_16x16x32_bf16 v[58:61], v[164:167], v[192:195], v[58:61]
	v_mfma_f32_16x16x32_bf16 v[46:49], v[156:159], v[200:203], v[46:49]
	v_mfma_f32_16x16x32_bf16 v[42:45], v[164:167], v[200:203], v[42:45]
	v_mfma_f32_16x16x32_bf16 v[34:37], v[156:159], v[208:211], v[34:37]
	v_mfma_f32_16x16x32_bf16 v[26:29], v[164:167], v[208:211], v[26:29]
	v_mfma_f32_16x16x32_bf16 v[18:21], v[156:159], v[216:219], v[18:21]
	v_mfma_f32_16x16x32_bf16 v[10:13], v[164:167], v[216:219], v[10:13]
	v_mfma_f32_16x16x32_bf16 v[54:57], v[168:171], v[188:191], v[54:57]
	v_mfma_f32_16x16x32_bf16 v[50:53], v[180:183], v[188:191], v[50:53]
	v_mfma_f32_16x16x32_bf16 v[38:41], v[168:171], v[196:199], v[38:41]
	v_mfma_f32_16x16x32_bf16 v[30:33], v[180:183], v[196:199], v[30:33]
	v_mfma_f32_16x16x32_bf16 v[22:25], v[168:171], v[204:207], v[22:25]
	v_mfma_f32_16x16x32_bf16 v[14:17], v[180:183], v[204:207], v[14:17]
	v_mfma_f32_16x16x32_bf16 v[6:9], v[168:171], v[212:215], v[6:9]
	v_mfma_f32_16x16x32_bf16 v[2:5], v[180:183], v[212:215], v[2:5]
	v_mfma_f32_16x16x32_bf16 v[54:57], v[172:175], v[192:195], v[54:57]
	v_mfma_f32_16x16x32_bf16 v[50:53], v[184:187], v[192:195], v[50:53]
	v_mfma_f32_16x16x32_bf16 v[38:41], v[172:175], v[200:203], v[38:41]
	v_mfma_f32_16x16x32_bf16 v[30:33], v[184:187], v[200:203], v[30:33]
	v_mfma_f32_16x16x32_bf16 v[22:25], v[172:175], v[208:211], v[22:25]
	v_mfma_f32_16x16x32_bf16 v[14:17], v[184:187], v[208:211], v[14:17]
	v_mfma_f32_16x16x32_bf16 v[6:9], v[172:175], v[216:219], v[6:9]
	v_mfma_f32_16x16x32_bf16 v[2:5], v[184:187], v[216:219], v[2:5]
	s_setprio 0
	s_barrier
	ds_read_b128 v[142:145], v153
	ds_read_b128 v[156:159], v153 offset:1024
	ds_read_b128 v[160:163], v153 offset:2048
	ds_read_b128 v[164:167], v153 offset:3072
	ds_read_b128 v[168:171], v154
	ds_read_b128 v[172:175], v154 offset:1024
	ds_read_b128 v[180:183], v154 offset:2048
	ds_read_b128 v[184:187], v154 offset:3072
	s_add_u32 s26, s26, 0xb0000
	s_addc_u32 s27, s27, 0
	s_mov_b32 m0, s29
	ds_read_b128 v[188:191], v152 offset:32768
	ds_read_b128 v[192:195], v152 offset:33792
	ds_read_b128 v[196:199], v152 offset:34816
	ds_read_b128 v[200:203], v152 offset:35840
	ds_read_b128 v[204:207], v152 offset:36864
	ds_read_b128 v[208:211], v152 offset:37888
	ds_read_b128 v[212:215], v152 offset:38912
	global_load_lds_dwordx4 v136, s[26:27]
	s_mov_b32 m0, s30
	ds_read_b128 v[216:219], v152 offset:39936
	global_load_lds_dwordx4 v132, s[26:27]
	s_waitcnt vmcnt(8)
	s_waitcnt lgkmcnt(0)
	s_barrier
	s_setprio 1
	v_mfma_f32_16x16x32_bf16 v[126:129], v[142:145], v[188:191], v[126:129]
	v_mfma_f32_16x16x32_bf16 v[122:125], v[160:163], v[188:191], v[122:125]
	v_mfma_f32_16x16x32_bf16 v[110:113], v[142:145], v[196:199], v[110:113]
	v_mfma_f32_16x16x32_bf16 v[106:109], v[160:163], v[196:199], v[106:109]
	v_mfma_f32_16x16x32_bf16 v[94:97], v[142:145], v[204:207], v[94:97]
	v_mfma_f32_16x16x32_bf16 v[90:93], v[160:163], v[204:207], v[90:93]
	v_mfma_f32_16x16x32_bf16 v[78:81], v[142:145], v[212:215], v[78:81]
	v_mfma_f32_16x16x32_bf16 v[74:77], v[160:163], v[212:215], v[74:77]
	v_mfma_f32_16x16x32_bf16 v[126:129], v[156:159], v[192:195], v[126:129]
	v_mfma_f32_16x16x32_bf16 v[122:125], v[164:167], v[192:195], v[122:125]
	v_mfma_f32_16x16x32_bf16 v[110:113], v[156:159], v[200:203], v[110:113]
	v_mfma_f32_16x16x32_bf16 v[106:109], v[164:167], v[200:203], v[106:109]
	v_mfma_f32_16x16x32_bf16 v[94:97], v[156:159], v[208:211], v[94:97]
	v_mfma_f32_16x16x32_bf16 v[90:93], v[164:167], v[208:211], v[90:93]
	v_mfma_f32_16x16x32_bf16 v[78:81], v[156:159], v[216:219], v[78:81]
	v_mfma_f32_16x16x32_bf16 v[74:77], v[164:167], v[216:219], v[74:77]
	v_mfma_f32_16x16x32_bf16 v[118:121], v[168:171], v[188:191], v[118:121]
	v_mfma_f32_16x16x32_bf16 v[114:117], v[180:183], v[188:191], v[114:117]
	v_mfma_f32_16x16x32_bf16 v[102:105], v[168:171], v[196:199], v[102:105]
	v_mfma_f32_16x16x32_bf16 v[98:101], v[180:183], v[196:199], v[98:101]
	v_mfma_f32_16x16x32_bf16 v[86:89], v[168:171], v[204:207], v[86:89]
	v_mfma_f32_16x16x32_bf16 v[82:85], v[180:183], v[204:207], v[82:85]
	v_mfma_f32_16x16x32_bf16 v[70:73], v[168:171], v[212:215], v[70:73]
	v_mfma_f32_16x16x32_bf16 v[66:69], v[180:183], v[212:215], v[66:69]
	v_mfma_f32_16x16x32_bf16 v[118:121], v[172:175], v[192:195], v[118:121]
	v_mfma_f32_16x16x32_bf16 v[114:117], v[184:187], v[192:195], v[114:117]
	v_mfma_f32_16x16x32_bf16 v[102:105], v[172:175], v[200:203], v[102:105]
	v_mfma_f32_16x16x32_bf16 v[98:101], v[184:187], v[200:203], v[98:101]
	v_mfma_f32_16x16x32_bf16 v[86:89], v[172:175], v[208:211], v[86:89]
	v_mfma_f32_16x16x32_bf16 v[82:85], v[184:187], v[208:211], v[82:85]
	v_mfma_f32_16x16x32_bf16 v[70:73], v[172:175], v[216:219], v[70:73]
	v_mfma_f32_16x16x32_bf16 v[66:69], v[184:187], v[216:219], v[66:69]
	s_setprio 0
	s_barrier
	s_mov_b32 m0, s42
	ds_read_b128 v[188:191], v152 offset:49152
	ds_read_b128 v[192:195], v152 offset:50176
	ds_read_b128 v[196:199], v152 offset:51200
	ds_read_b128 v[200:203], v152 offset:52224
	s_add_u32 s98, s24, 0x80
	s_addc_u32 s99, s25, 0
	global_load_lds_dwordx4 v134, s[98:99]
	s_mov_b32 m0, s43
	s_add_u32 s24, s24, 0xb0080
	s_addc_u32 s25, s25, 0
	global_load_lds_dwordx4 v130, s[98:99]
	s_mov_b32 m0, s44
	ds_read_b128 v[204:207], v152 offset:53248
	global_load_lds_dwordx4 v134, s[24:25]
	s_mov_b32 m0, s45
	ds_read_b128 v[208:211], v152 offset:54272
	global_load_lds_dwordx4 v130, s[24:25]
	s_add_u32 s98, s26, 0xfff50080
	s_addc_u32 s99, s27, -1
	s_mov_b32 m0, s0
	ds_read_b128 v[212:215], v152 offset:55296
	global_load_lds_dwordx4 v136, s[98:99]
	s_mov_b32 m0, s1
	ds_read_b128 v[216:219], v152 offset:56320
	global_load_lds_dwordx4 v132, s[98:99]
	s_waitcnt vmcnt(8)
	s_waitcnt lgkmcnt(0)
	s_barrier
	s_setprio 1
	v_mfma_f32_16x16x32_bf16 v[62:65], v[142:145], v[188:191], v[62:65]
	v_mfma_f32_16x16x32_bf16 v[58:61], v[160:163], v[188:191], v[58:61]
	v_mfma_f32_16x16x32_bf16 v[46:49], v[142:145], v[196:199], v[46:49]
	v_mfma_f32_16x16x32_bf16 v[42:45], v[160:163], v[196:199], v[42:45]
	v_mfma_f32_16x16x32_bf16 v[34:37], v[142:145], v[204:207], v[34:37]
	v_mfma_f32_16x16x32_bf16 v[26:29], v[160:163], v[204:207], v[26:29]
	v_mfma_f32_16x16x32_bf16 v[18:21], v[142:145], v[212:215], v[18:21]
	v_mfma_f32_16x16x32_bf16 v[10:13], v[160:163], v[212:215], v[10:13]
	v_mfma_f32_16x16x32_bf16 v[62:65], v[156:159], v[192:195], v[62:65]
	v_mfma_f32_16x16x32_bf16 v[58:61], v[164:167], v[192:195], v[58:61]
	v_mfma_f32_16x16x32_bf16 v[46:49], v[156:159], v[200:203], v[46:49]
	v_mfma_f32_16x16x32_bf16 v[42:45], v[164:167], v[200:203], v[42:45]
	v_mfma_f32_16x16x32_bf16 v[34:37], v[156:159], v[208:211], v[34:37]
	v_mfma_f32_16x16x32_bf16 v[26:29], v[164:167], v[208:211], v[26:29]
	v_mfma_f32_16x16x32_bf16 v[18:21], v[156:159], v[216:219], v[18:21]
	v_mfma_f32_16x16x32_bf16 v[10:13], v[164:167], v[216:219], v[10:13]
	v_mfma_f32_16x16x32_bf16 v[54:57], v[168:171], v[188:191], v[54:57]
	v_mfma_f32_16x16x32_bf16 v[50:53], v[180:183], v[188:191], v[50:53]
	v_mfma_f32_16x16x32_bf16 v[38:41], v[168:171], v[196:199], v[38:41]
	v_mfma_f32_16x16x32_bf16 v[30:33], v[180:183], v[196:199], v[30:33]
	v_mfma_f32_16x16x32_bf16 v[22:25], v[168:171], v[204:207], v[22:25]
	v_mfma_f32_16x16x32_bf16 v[14:17], v[180:183], v[204:207], v[14:17]
	v_mfma_f32_16x16x32_bf16 v[6:9], v[168:171], v[212:215], v[6:9]
	v_mfma_f32_16x16x32_bf16 v[2:5], v[180:183], v[212:215], v[2:5]
	v_mfma_f32_16x16x32_bf16 v[54:57], v[172:175], v[192:195], v[54:57]
	v_mfma_f32_16x16x32_bf16 v[50:53], v[184:187], v[192:195], v[50:53]
	v_mfma_f32_16x16x32_bf16 v[38:41], v[172:175], v[200:203], v[38:41]
	v_mfma_f32_16x16x32_bf16 v[30:33], v[184:187], v[200:203], v[30:33]
	v_mfma_f32_16x16x32_bf16 v[22:25], v[172:175], v[208:211], v[22:25]
	v_mfma_f32_16x16x32_bf16 v[14:17], v[184:187], v[208:211], v[14:17]
	v_mfma_f32_16x16x32_bf16 v[6:9], v[172:175], v[216:219], v[6:9]
	v_mfma_f32_16x16x32_bf16 v[2:5], v[184:187], v[216:219], v[2:5]
	s_setprio 0
	s_barrier
	s_add_i32 s51, s51, 2
	s_add_u32 s22, s22, 0x100
	s_addc_u32 s23, s23, 0
	s_add_u32 s49, s49, 0x100
	s_addc_u32 s50, s50, 0
	s_cmp_gt_u32 s51, 41
	s_cbranch_scc0 .LBB0_1108
